# RWKV scan phase: producer global loads prefetched one chunk ahead, consumer loop hand-scheduled (LDS reads 2 steps ahead), conflict-free nw LDS layout, DPP instead of ds_bpermute reductions
# speedup vs baseline: 1.0198x; 1.0198x over previous
.LBB0_1250:
	s_mov_b64 s[8:9], s[0:1]
	s_waitcnt vmcnt(7)
	v_mov_b32_e32 v48, v154
	v_mov_b32_e32 v0, v154
	s_mov_b32 s40, s33
	v_readfirstlane_b32 s4, v0
	s_ashr_i32 s10, s4, 6
	v_mov_b32_e32 v0, v154
	s_cmp_lt_i32 s10, 4
	v_and_b32_e32 v88, 63, v0
	s_mov_b64 s[4:5], -1
	s_cbranch_scc0 .LBB0_1254
	s_lshl_b32 s4, s10, 11
	s_add_i32 s4, s4, 0
	v_and_b32_e32 v3, 3, v0
	s_load_dwordx2 s[6:7], s[8:9], 0x138
	s_add_i32 s37, s4, 0x15800
	v_and_b32_e32 v4, 48, v0
	v_lshlrev_b32_e32 v3, 2, v3
	v_lshrrev_b32_e32 v1, 4, v88
	s_lshl_b32 s4, s64, 11
	s_lshl_b32 s36, s10, 2
	v_add3_u32 v9, s37, v4, v3
	v_lshlrev_b32_e32 v3, 5, v88
	v_and_b32_e32 v2, 15, v0
	s_ashr_i32 s5, s4, 31
	v_and_b32_e32 v4, 0x7c0, v3
	v_or_b32_e32 v12, s36, v1
	v_and_b32_e32 v1, 62, v0
	v_and_b32_e32 v0, 1, v0
	s_lshl_b64 s[34:35], s[4:5], 5
	v_add_u32_e32 v4, s37, v4
	s_ashr_i32 s37, s36, 31
	v_lshlrev_b32_e32 v1, 4, v1
	v_lshlrev_b32_e32 v0, 2, v0
	v_or3_b32 v0, s34, v1, v0
	v_mov_b32_e32 v1, s35
	s_lshl_b64 s[34:35], s[36:37], 1
	s_waitcnt lgkmcnt(0)
	s_add_u32 s6, s6, s34
	s_addc_u32 s7, s7, s35
	v_lshlrev_b32_e32 v7, 3, v2
	v_and_b32_e32 v3, 32, v3
	v_lshlrev_b32_e32 v10, 4, v2
	v_lshl_add_u64 v[0:1], s[6:7], 0, v[0:1]
	v_mov_b32_e32 v2, 0
	s_mov_b32 s4, 0
	v_sub_u32_e32 v11, 0, v10
	v_lshl_add_u64 v[0:1], v[0:1], 0, s[12:13]
	v_add_u32_e32 v13, v4, v3
	v_add_u32_e32 v14, 0x400, v9
	v_and_b32_e32 v15, 12, v88
	v_lshlrev_b32_e32 v8, 2, v88
	v_add_u32_e32 v8, 0x20000, v8
	v_cmp_ne_u32_e32 vcc, 0, v15
	s_nop 1
	v_cndmask_b32_e32 v9, v9, v8, vcc
	v_mov_b32_e32 v3, v2
	v_mov_b32_e32 v4, v2
	v_mov_b32_e32 v5, v2
.LBB0_1252:
	s_and_b32 s5, s4, 32
	s_mulk_i32 s5, 0x560
	s_add_i32 s5, s5, 0
	s_barrier
	v_lshl_add_u32 v16, v7, 2, s5
	v_lshl_add_u32 v18, v12, 2, s5
	v_mov_b32_e32 v19, s5
	v_add_u32_e32 v17, v16, v11
	ds_read_b128 v[100:103], v17 offset:0
	ds_read_b128 v[104:107], v17 offset:256
	ds_read_b128 v[116:119], v17 offset:1024
	ds_read_b128 v[108:111], v17 offset:512
	ds_read_b128 v[112:115], v17 offset:768
	ds_read_b32 v120, v18 offset:1280
	ds_read_b64 v[122:123], v19 offset:1344
	ds_read_b128 v[156:159], v17 offset:1376
	ds_read_b128 v[160:163], v17 offset:1632
	ds_read_b128 v[172:175], v17 offset:2400
	ds_read_b128 v[164:167], v17 offset:1888
	ds_read_b128 v[168:171], v17 offset:2144
	ds_read_b32 v176, v18 offset:2656
	ds_read_b64 v[178:179], v19 offset:2720
	s_waitcnt lgkmcnt(7)
	ds_read_b128 v[180:183], v17 offset:2752
	ds_read_b128 v[184:187], v17 offset:3008
	ds_read_b128 v[196:199], v17 offset:3776
	ds_read_b128 v[188:191], v17 offset:3264
	ds_read_b128 v[192:195], v17 offset:3520
	v_pk_mul_f32 v[20:21], v[2:3], v[100:101] op_sel_hi:[0,1]
	v_pk_fma_f32 v[20:21], v[102:103], v[2:3], v[20:21] op_sel:[0,1,0]
	v_pk_fma_f32 v[20:21], v[104:105], v[4:5], v[20:21] op_sel_hi:[1,0,1]
	v_pk_fma_f32 v[20:21], v[106:107], v[4:5], v[20:21] op_sel:[0,1,0]
	v_pk_mul_f32 v[22:23], v[116:117], v[120:121] op_sel_hi:[1,0]
	v_pk_mul_f32 v[24:25], v[118:119], v[120:121] op_sel_hi:[1,0]
	v_add_f32_dpp v26, v20, v20 row_ror:8 row_mask:0xf bank_mask:0xf bound_ctrl:1
	v_add_f32_dpp v28, v21, v21 row_ror:8 row_mask:0xf bank_mask:0xf bound_ctrl:1
	v_pk_fma_f32 v[22:23], v[2:3], v[108:109], v[22:23]
	v_add_f32_dpp v26, v26, v26 row_ror:4 row_mask:0xf bank_mask:0xf bound_ctrl:1
	v_pk_fma_f32 v[24:25], v[4:5], v[110:111], v[24:25]
	v_add_f32_dpp v28, v28, v28 row_ror:4 row_mask:0xf bank_mask:0xf bound_ctrl:1
	v_add_f32_dpp v26, v26, v26 row_ror:2 row_mask:0xf bank_mask:0xf bound_ctrl:1
	ds_read_b32 v200, v18 offset:4032
	ds_read_b64 v[202:203], v19 offset:4096
	v_add_f32_dpp v26, v26, v26 row_ror:1 row_mask:0xf bank_mask:0xf bound_ctrl:1
	v_pk_fma_f32 v[2:3], v[112:113], v[26:27], v[22:23] op_sel_hi:[1,0,1]
	v_pk_fma_f32 v[4:5], v[114:115], v[26:27], v[24:25] op_sel_hi:[1,0,1]
	v_mul_f32_e32 v29, v122, v26
	v_fmac_f32_e32 v29, v120, v123
	v_fmac_f32_e32 v28, 0x3e800000, v29
	ds_write_b32 v9, v28
	s_waitcnt lgkmcnt(8)
	ds_read_b128 v[100:103], v17 offset:4128
	ds_read_b128 v[104:107], v17 offset:4384
	ds_read_b128 v[116:119], v17 offset:5152
	ds_read_b128 v[108:111], v17 offset:4640
	ds_read_b128 v[112:115], v17 offset:4896
	v_pk_mul_f32 v[20:21], v[2:3], v[156:157] op_sel_hi:[0,1]
	v_pk_fma_f32 v[20:21], v[158:159], v[2:3], v[20:21] op_sel:[0,1,0]
	v_pk_fma_f32 v[20:21], v[160:161], v[4:5], v[20:21] op_sel_hi:[1,0,1]
	v_pk_fma_f32 v[20:21], v[162:163], v[4:5], v[20:21] op_sel:[0,1,0]
	v_pk_mul_f32 v[22:23], v[172:173], v[176:177] op_sel_hi:[1,0]
	v_pk_mul_f32 v[24:25], v[174:175], v[176:177] op_sel_hi:[1,0]
	v_add_f32_dpp v26, v20, v20 row_ror:8 row_mask:0xf bank_mask:0xf bound_ctrl:1
	v_add_f32_dpp v28, v21, v21 row_ror:8 row_mask:0xf bank_mask:0xf bound_ctrl:1
	v_pk_fma_f32 v[22:23], v[2:3], v[164:165], v[22:23]
	v_add_f32_dpp v26, v26, v26 row_ror:4 row_mask:0xf bank_mask:0xf bound_ctrl:1
	v_pk_fma_f32 v[24:25], v[4:5], v[166:167], v[24:25]
	v_add_f32_dpp v28, v28, v28 row_ror:4 row_mask:0xf bank_mask:0xf bound_ctrl:1
	v_add_f32_dpp v26, v26, v26 row_ror:2 row_mask:0xf bank_mask:0xf bound_ctrl:1
	ds_read_b32 v120, v18 offset:5408
	ds_read_b64 v[122:123], v19 offset:5472
	v_add_f32_dpp v26, v26, v26 row_ror:1 row_mask:0xf bank_mask:0xf bound_ctrl:1
	v_pk_fma_f32 v[2:3], v[168:169], v[26:27], v[22:23] op_sel_hi:[1,0,1]
	v_pk_fma_f32 v[4:5], v[170:171], v[26:27], v[24:25] op_sel_hi:[1,0,1]
	v_mul_f32_e32 v29, v178, v26
	v_fmac_f32_e32 v29, v176, v179
	v_fmac_f32_e32 v28, 0x3e800000, v29
	ds_write_b32 v9, v28 offset:64
	s_waitcnt lgkmcnt(9)
	ds_read_b128 v[156:159], v17 offset:5504
	ds_read_b128 v[160:163], v17 offset:5760
	ds_read_b128 v[172:175], v17 offset:6528
	ds_read_b128 v[164:167], v17 offset:6016
	ds_read_b128 v[168:171], v17 offset:6272
	v_pk_mul_f32 v[20:21], v[2:3], v[180:181] op_sel_hi:[0,1]
	v_pk_fma_f32 v[20:21], v[182:183], v[2:3], v[20:21] op_sel:[0,1,0]
	v_pk_fma_f32 v[20:21], v[184:185], v[4:5], v[20:21] op_sel_hi:[1,0,1]
	v_pk_fma_f32 v[20:21], v[186:187], v[4:5], v[20:21] op_sel:[0,1,0]
	v_pk_mul_f32 v[22:23], v[196:197], v[200:201] op_sel_hi:[1,0]
	v_pk_mul_f32 v[24:25], v[198:199], v[200:201] op_sel_hi:[1,0]
	v_add_f32_dpp v26, v20, v20 row_ror:8 row_mask:0xf bank_mask:0xf bound_ctrl:1
	v_add_f32_dpp v28, v21, v21 row_ror:8 row_mask:0xf bank_mask:0xf bound_ctrl:1
	v_pk_fma_f32 v[22:23], v[2:3], v[188:189], v[22:23]
	v_add_f32_dpp v26, v26, v26 row_ror:4 row_mask:0xf bank_mask:0xf bound_ctrl:1
	v_pk_fma_f32 v[24:25], v[4:5], v[190:191], v[24:25]
	v_add_f32_dpp v28, v28, v28 row_ror:4 row_mask:0xf bank_mask:0xf bound_ctrl:1
	v_add_f32_dpp v26, v26, v26 row_ror:2 row_mask:0xf bank_mask:0xf bound_ctrl:1
	ds_read_b32 v176, v18 offset:6784
	ds_read_b64 v[178:179], v19 offset:6848
	v_add_f32_dpp v26, v26, v26 row_ror:1 row_mask:0xf bank_mask:0xf bound_ctrl:1
	v_pk_fma_f32 v[2:3], v[192:193], v[26:27], v[22:23] op_sel_hi:[1,0,1]
	v_pk_fma_f32 v[4:5], v[194:195], v[26:27], v[24:25] op_sel_hi:[1,0,1]
	v_mul_f32_e32 v29, v202, v26
	v_fmac_f32_e32 v29, v200, v203
	v_fmac_f32_e32 v28, 0x3e800000, v29
	ds_write_b32 v9, v28 offset:128
	s_waitcnt lgkmcnt(9)
	ds_read_b128 v[180:183], v17 offset:6880
	ds_read_b128 v[184:187], v17 offset:7136
	ds_read_b128 v[196:199], v17 offset:7904
	ds_read_b128 v[188:191], v17 offset:7392
	ds_read_b128 v[192:195], v17 offset:7648
	v_pk_mul_f32 v[20:21], v[2:3], v[100:101] op_sel_hi:[0,1]
	v_pk_fma_f32 v[20:21], v[102:103], v[2:3], v[20:21] op_sel:[0,1,0]
	v_pk_fma_f32 v[20:21], v[104:105], v[4:5], v[20:21] op_sel_hi:[1,0,1]
	v_pk_fma_f32 v[20:21], v[106:107], v[4:5], v[20:21] op_sel:[0,1,0]
	v_pk_mul_f32 v[22:23], v[116:117], v[120:121] op_sel_hi:[1,0]
	v_pk_mul_f32 v[24:25], v[118:119], v[120:121] op_sel_hi:[1,0]
	v_add_f32_dpp v26, v20, v20 row_ror:8 row_mask:0xf bank_mask:0xf bound_ctrl:1
	v_add_f32_dpp v28, v21, v21 row_ror:8 row_mask:0xf bank_mask:0xf bound_ctrl:1
	v_pk_fma_f32 v[22:23], v[2:3], v[108:109], v[22:23]
	v_add_f32_dpp v26, v26, v26 row_ror:4 row_mask:0xf bank_mask:0xf bound_ctrl:1
	v_pk_fma_f32 v[24:25], v[4:5], v[110:111], v[24:25]
	v_add_f32_dpp v28, v28, v28 row_ror:4 row_mask:0xf bank_mask:0xf bound_ctrl:1
	v_add_f32_dpp v26, v26, v26 row_ror:2 row_mask:0xf bank_mask:0xf bound_ctrl:1
	ds_read_b32 v200, v18 offset:8160
	ds_read_b64 v[202:203], v19 offset:8224
	v_add_f32_dpp v26, v26, v26 row_ror:1 row_mask:0xf bank_mask:0xf bound_ctrl:1
	v_pk_fma_f32 v[2:3], v[112:113], v[26:27], v[22:23] op_sel_hi:[1,0,1]
	v_pk_fma_f32 v[4:5], v[114:115], v[26:27], v[24:25] op_sel_hi:[1,0,1]
	v_mul_f32_e32 v29, v122, v26
	v_fmac_f32_e32 v29, v120, v123
	v_fmac_f32_e32 v28, 0x3e800000, v29
	ds_write_b32 v9, v28 offset:192
	s_waitcnt lgkmcnt(9)
	ds_read_b128 v[100:103], v17 offset:8256
	ds_read_b128 v[104:107], v17 offset:8512
	ds_read_b128 v[116:119], v17 offset:9280
	ds_read_b128 v[108:111], v17 offset:8768
	ds_read_b128 v[112:115], v17 offset:9024
	v_pk_mul_f32 v[20:21], v[2:3], v[156:157] op_sel_hi:[0,1]
	v_pk_fma_f32 v[20:21], v[158:159], v[2:3], v[20:21] op_sel:[0,1,0]
	v_pk_fma_f32 v[20:21], v[160:161], v[4:5], v[20:21] op_sel_hi:[1,0,1]
	v_pk_fma_f32 v[20:21], v[162:163], v[4:5], v[20:21] op_sel:[0,1,0]
	v_pk_mul_f32 v[22:23], v[172:173], v[176:177] op_sel_hi:[1,0]
	v_pk_mul_f32 v[24:25], v[174:175], v[176:177] op_sel_hi:[1,0]
	v_add_f32_dpp v26, v20, v20 row_ror:8 row_mask:0xf bank_mask:0xf bound_ctrl:1
	v_add_f32_dpp v28, v21, v21 row_ror:8 row_mask:0xf bank_mask:0xf bound_ctrl:1
	v_pk_fma_f32 v[22:23], v[2:3], v[164:165], v[22:23]
	v_add_f32_dpp v26, v26, v26 row_ror:4 row_mask:0xf bank_mask:0xf bound_ctrl:1
	v_pk_fma_f32 v[24:25], v[4:5], v[166:167], v[24:25]
	v_add_f32_dpp v28, v28, v28 row_ror:4 row_mask:0xf bank_mask:0xf bound_ctrl:1
	v_add_f32_dpp v26, v26, v26 row_ror:2 row_mask:0xf bank_mask:0xf bound_ctrl:1
	ds_read_b32 v120, v18 offset:9536
	ds_read_b64 v[122:123], v19 offset:9600
	v_add_f32_dpp v26, v26, v26 row_ror:1 row_mask:0xf bank_mask:0xf bound_ctrl:1
	v_pk_fma_f32 v[2:3], v[168:169], v[26:27], v[22:23] op_sel_hi:[1,0,1]
	v_pk_fma_f32 v[4:5], v[170:171], v[26:27], v[24:25] op_sel_hi:[1,0,1]
	v_mul_f32_e32 v29, v178, v26
	v_fmac_f32_e32 v29, v176, v179
	v_fmac_f32_e32 v28, 0x3e800000, v29
	ds_write_b32 v9, v28 offset:256
	s_waitcnt lgkmcnt(9)
	ds_read_b128 v[156:159], v17 offset:9632
	ds_read_b128 v[160:163], v17 offset:9888
	ds_read_b128 v[172:175], v17 offset:10656
	ds_read_b128 v[164:167], v17 offset:10144
	ds_read_b128 v[168:171], v17 offset:10400
	v_pk_mul_f32 v[20:21], v[2:3], v[180:181] op_sel_hi:[0,1]
	v_pk_fma_f32 v[20:21], v[182:183], v[2:3], v[20:21] op_sel:[0,1,0]
	v_pk_fma_f32 v[20:21], v[184:185], v[4:5], v[20:21] op_sel_hi:[1,0,1]
	v_pk_fma_f32 v[20:21], v[186:187], v[4:5], v[20:21] op_sel:[0,1,0]
	v_pk_mul_f32 v[22:23], v[196:197], v[200:201] op_sel_hi:[1,0]
	v_pk_mul_f32 v[24:25], v[198:199], v[200:201] op_sel_hi:[1,0]
	v_add_f32_dpp v26, v20, v20 row_ror:8 row_mask:0xf bank_mask:0xf bound_ctrl:1
	v_add_f32_dpp v28, v21, v21 row_ror:8 row_mask:0xf bank_mask:0xf bound_ctrl:1
	v_pk_fma_f32 v[22:23], v[2:3], v[188:189], v[22:23]
	v_add_f32_dpp v26, v26, v26 row_ror:4 row_mask:0xf bank_mask:0xf bound_ctrl:1
	v_pk_fma_f32 v[24:25], v[4:5], v[190:191], v[24:25]
	v_add_f32_dpp v28, v28, v28 row_ror:4 row_mask:0xf bank_mask:0xf bound_ctrl:1
	v_add_f32_dpp v26, v26, v26 row_ror:2 row_mask:0xf bank_mask:0xf bound_ctrl:1
	ds_read_b32 v176, v18 offset:10912
	ds_read_b64 v[178:179], v19 offset:10976
	v_add_f32_dpp v26, v26, v26 row_ror:1 row_mask:0xf bank_mask:0xf bound_ctrl:1
	v_pk_fma_f32 v[2:3], v[192:193], v[26:27], v[22:23] op_sel_hi:[1,0,1]
	v_pk_fma_f32 v[4:5], v[194:195], v[26:27], v[24:25] op_sel_hi:[1,0,1]
	v_mul_f32_e32 v29, v202, v26
	v_fmac_f32_e32 v29, v200, v203
	v_fmac_f32_e32 v28, 0x3e800000, v29
	ds_write_b32 v9, v28 offset:320
	s_waitcnt lgkmcnt(9)
	ds_read_b128 v[180:183], v17 offset:11008
	ds_read_b128 v[184:187], v17 offset:11264
	ds_read_b128 v[196:199], v17 offset:12032
	ds_read_b128 v[188:191], v17 offset:11520
	ds_read_b128 v[192:195], v17 offset:11776
	v_pk_mul_f32 v[20:21], v[2:3], v[100:101] op_sel_hi:[0,1]
	v_pk_fma_f32 v[20:21], v[102:103], v[2:3], v[20:21] op_sel:[0,1,0]
	v_pk_fma_f32 v[20:21], v[104:105], v[4:5], v[20:21] op_sel_hi:[1,0,1]
	v_pk_fma_f32 v[20:21], v[106:107], v[4:5], v[20:21] op_sel:[0,1,0]
	v_pk_mul_f32 v[22:23], v[116:117], v[120:121] op_sel_hi:[1,0]
	v_pk_mul_f32 v[24:25], v[118:119], v[120:121] op_sel_hi:[1,0]
	v_add_f32_dpp v26, v20, v20 row_ror:8 row_mask:0xf bank_mask:0xf bound_ctrl:1
	v_add_f32_dpp v28, v21, v21 row_ror:8 row_mask:0xf bank_mask:0xf bound_ctrl:1
	v_pk_fma_f32 v[22:23], v[2:3], v[108:109], v[22:23]
	v_add_f32_dpp v26, v26, v26 row_ror:4 row_mask:0xf bank_mask:0xf bound_ctrl:1
	v_pk_fma_f32 v[24:25], v[4:5], v[110:111], v[24:25]
	v_add_f32_dpp v28, v28, v28 row_ror:4 row_mask:0xf bank_mask:0xf bound_ctrl:1
	v_add_f32_dpp v26, v26, v26 row_ror:2 row_mask:0xf bank_mask:0xf bound_ctrl:1
	ds_read_b32 v200, v18 offset:12288
	ds_read_b64 v[202:203], v19 offset:12352
	v_add_f32_dpp v26, v26, v26 row_ror:1 row_mask:0xf bank_mask:0xf bound_ctrl:1
	v_pk_fma_f32 v[2:3], v[112:113], v[26:27], v[22:23] op_sel_hi:[1,0,1]
	v_pk_fma_f32 v[4:5], v[114:115], v[26:27], v[24:25] op_sel_hi:[1,0,1]
	v_mul_f32_e32 v29, v122, v26
	v_fmac_f32_e32 v29, v120, v123
	v_fmac_f32_e32 v28, 0x3e800000, v29
	ds_write_b32 v9, v28 offset:384
	s_waitcnt lgkmcnt(9)
	ds_read_b128 v[100:103], v17 offset:12384
	ds_read_b128 v[104:107], v17 offset:12640
	ds_read_b128 v[116:119], v17 offset:13408
	ds_read_b128 v[108:111], v17 offset:12896
	ds_read_b128 v[112:115], v17 offset:13152
	v_pk_mul_f32 v[20:21], v[2:3], v[156:157] op_sel_hi:[0,1]
	v_pk_fma_f32 v[20:21], v[158:159], v[2:3], v[20:21] op_sel:[0,1,0]
	v_pk_fma_f32 v[20:21], v[160:161], v[4:5], v[20:21] op_sel_hi:[1,0,1]
	v_pk_fma_f32 v[20:21], v[162:163], v[4:5], v[20:21] op_sel:[0,1,0]
	v_pk_mul_f32 v[22:23], v[172:173], v[176:177] op_sel_hi:[1,0]
	v_pk_mul_f32 v[24:25], v[174:175], v[176:177] op_sel_hi:[1,0]
	v_add_f32_dpp v26, v20, v20 row_ror:8 row_mask:0xf bank_mask:0xf bound_ctrl:1
	v_add_f32_dpp v28, v21, v21 row_ror:8 row_mask:0xf bank_mask:0xf bound_ctrl:1
	v_pk_fma_f32 v[22:23], v[2:3], v[164:165], v[22:23]
	v_add_f32_dpp v26, v26, v26 row_ror:4 row_mask:0xf bank_mask:0xf bound_ctrl:1
	v_pk_fma_f32 v[24:25], v[4:5], v[166:167], v[24:25]
	v_add_f32_dpp v28, v28, v28 row_ror:4 row_mask:0xf bank_mask:0xf bound_ctrl:1
	v_add_f32_dpp v26, v26, v26 row_ror:2 row_mask:0xf bank_mask:0xf bound_ctrl:1
	ds_read_b32 v120, v18 offset:13664
	ds_read_b64 v[122:123], v19 offset:13728
	v_add_f32_dpp v26, v26, v26 row_ror:1 row_mask:0xf bank_mask:0xf bound_ctrl:1
	v_pk_fma_f32 v[2:3], v[168:169], v[26:27], v[22:23] op_sel_hi:[1,0,1]
	v_pk_fma_f32 v[4:5], v[170:171], v[26:27], v[24:25] op_sel_hi:[1,0,1]
	v_mul_f32_e32 v29, v178, v26
	v_fmac_f32_e32 v29, v176, v179
	v_fmac_f32_e32 v28, 0x3e800000, v29
	ds_write_b32 v9, v28 offset:448
	s_waitcnt lgkmcnt(9)
	ds_read_b128 v[156:159], v17 offset:13760
	ds_read_b128 v[160:163], v17 offset:14016
	ds_read_b128 v[172:175], v17 offset:14784
	ds_read_b128 v[164:167], v17 offset:14272
	ds_read_b128 v[168:171], v17 offset:14528
	v_pk_mul_f32 v[20:21], v[2:3], v[180:181] op_sel_hi:[0,1]
	v_pk_fma_f32 v[20:21], v[182:183], v[2:3], v[20:21] op_sel:[0,1,0]
	v_pk_fma_f32 v[20:21], v[184:185], v[4:5], v[20:21] op_sel_hi:[1,0,1]
	v_pk_fma_f32 v[20:21], v[186:187], v[4:5], v[20:21] op_sel:[0,1,0]
	v_pk_mul_f32 v[22:23], v[196:197], v[200:201] op_sel_hi:[1,0]
	v_pk_mul_f32 v[24:25], v[198:199], v[200:201] op_sel_hi:[1,0]
	v_add_f32_dpp v26, v20, v20 row_ror:8 row_mask:0xf bank_mask:0xf bound_ctrl:1
	v_add_f32_dpp v28, v21, v21 row_ror:8 row_mask:0xf bank_mask:0xf bound_ctrl:1
	v_pk_fma_f32 v[22:23], v[2:3], v[188:189], v[22:23]
	v_add_f32_dpp v26, v26, v26 row_ror:4 row_mask:0xf bank_mask:0xf bound_ctrl:1
	v_pk_fma_f32 v[24:25], v[4:5], v[190:191], v[24:25]
	v_add_f32_dpp v28, v28, v28 row_ror:4 row_mask:0xf bank_mask:0xf bound_ctrl:1
	v_add_f32_dpp v26, v26, v26 row_ror:2 row_mask:0xf bank_mask:0xf bound_ctrl:1
	ds_read_b32 v176, v18 offset:15040
	ds_read_b64 v[178:179], v19 offset:15104
	v_add_f32_dpp v26, v26, v26 row_ror:1 row_mask:0xf bank_mask:0xf bound_ctrl:1
	v_pk_fma_f32 v[2:3], v[192:193], v[26:27], v[22:23] op_sel_hi:[1,0,1]
	v_pk_fma_f32 v[4:5], v[194:195], v[26:27], v[24:25] op_sel_hi:[1,0,1]
	v_mul_f32_e32 v29, v202, v26
	v_fmac_f32_e32 v29, v200, v203
	v_fmac_f32_e32 v28, 0x3e800000, v29
	ds_write_b32 v9, v28 offset:512
	s_waitcnt lgkmcnt(9)
	ds_read_b128 v[180:183], v17 offset:15136
	ds_read_b128 v[184:187], v17 offset:15392
	ds_read_b128 v[196:199], v17 offset:16160
	ds_read_b128 v[188:191], v17 offset:15648
	ds_read_b128 v[192:195], v17 offset:15904
	v_pk_mul_f32 v[20:21], v[2:3], v[100:101] op_sel_hi:[0,1]
	v_pk_fma_f32 v[20:21], v[102:103], v[2:3], v[20:21] op_sel:[0,1,0]
	v_pk_fma_f32 v[20:21], v[104:105], v[4:5], v[20:21] op_sel_hi:[1,0,1]
	v_pk_fma_f32 v[20:21], v[106:107], v[4:5], v[20:21] op_sel:[0,1,0]
	v_pk_mul_f32 v[22:23], v[116:117], v[120:121] op_sel_hi:[1,0]
	v_pk_mul_f32 v[24:25], v[118:119], v[120:121] op_sel_hi:[1,0]
	v_add_f32_dpp v26, v20, v20 row_ror:8 row_mask:0xf bank_mask:0xf bound_ctrl:1
	v_add_f32_dpp v28, v21, v21 row_ror:8 row_mask:0xf bank_mask:0xf bound_ctrl:1
	v_pk_fma_f32 v[22:23], v[2:3], v[108:109], v[22:23]
	v_add_f32_dpp v26, v26, v26 row_ror:4 row_mask:0xf bank_mask:0xf bound_ctrl:1
	v_pk_fma_f32 v[24:25], v[4:5], v[110:111], v[24:25]
	v_add_f32_dpp v28, v28, v28 row_ror:4 row_mask:0xf bank_mask:0xf bound_ctrl:1
	v_add_f32_dpp v26, v26, v26 row_ror:2 row_mask:0xf bank_mask:0xf bound_ctrl:1
	ds_read_b32 v200, v18 offset:16416
	ds_read_b64 v[202:203], v19 offset:16480
	v_add_f32_dpp v26, v26, v26 row_ror:1 row_mask:0xf bank_mask:0xf bound_ctrl:1
	v_pk_fma_f32 v[2:3], v[112:113], v[26:27], v[22:23] op_sel_hi:[1,0,1]
	v_pk_fma_f32 v[4:5], v[114:115], v[26:27], v[24:25] op_sel_hi:[1,0,1]
	v_mul_f32_e32 v29, v122, v26
	v_fmac_f32_e32 v29, v120, v123
	v_fmac_f32_e32 v28, 0x3e800000, v29
	ds_write_b32 v9, v28 offset:576
	s_waitcnt lgkmcnt(9)
	ds_read_b128 v[100:103], v17 offset:16512
	ds_read_b128 v[104:107], v17 offset:16768
	ds_read_b128 v[116:119], v17 offset:17536
	ds_read_b128 v[108:111], v17 offset:17024
	ds_read_b128 v[112:115], v17 offset:17280
	v_pk_mul_f32 v[20:21], v[2:3], v[156:157] op_sel_hi:[0,1]
	v_pk_fma_f32 v[20:21], v[158:159], v[2:3], v[20:21] op_sel:[0,1,0]
	v_pk_fma_f32 v[20:21], v[160:161], v[4:5], v[20:21] op_sel_hi:[1,0,1]
	v_pk_fma_f32 v[20:21], v[162:163], v[4:5], v[20:21] op_sel:[0,1,0]
	v_pk_mul_f32 v[22:23], v[172:173], v[176:177] op_sel_hi:[1,0]
	v_pk_mul_f32 v[24:25], v[174:175], v[176:177] op_sel_hi:[1,0]
	v_add_f32_dpp v26, v20, v20 row_ror:8 row_mask:0xf bank_mask:0xf bound_ctrl:1
	v_add_f32_dpp v28, v21, v21 row_ror:8 row_mask:0xf bank_mask:0xf bound_ctrl:1
	v_pk_fma_f32 v[22:23], v[2:3], v[164:165], v[22:23]
	v_add_f32_dpp v26, v26, v26 row_ror:4 row_mask:0xf bank_mask:0xf bound_ctrl:1
	v_pk_fma_f32 v[24:25], v[4:5], v[166:167], v[24:25]
	v_add_f32_dpp v28, v28, v28 row_ror:4 row_mask:0xf bank_mask:0xf bound_ctrl:1
	v_add_f32_dpp v26, v26, v26 row_ror:2 row_mask:0xf bank_mask:0xf bound_ctrl:1
	ds_read_b32 v120, v18 offset:17792
	ds_read_b64 v[122:123], v19 offset:17856
	v_add_f32_dpp v26, v26, v26 row_ror:1 row_mask:0xf bank_mask:0xf bound_ctrl:1
	v_pk_fma_f32 v[2:3], v[168:169], v[26:27], v[22:23] op_sel_hi:[1,0,1]
	v_pk_fma_f32 v[4:5], v[170:171], v[26:27], v[24:25] op_sel_hi:[1,0,1]
	v_mul_f32_e32 v29, v178, v26
	v_fmac_f32_e32 v29, v176, v179
	v_fmac_f32_e32 v28, 0x3e800000, v29
	ds_write_b32 v9, v28 offset:640
	s_waitcnt lgkmcnt(9)
	ds_read_b128 v[156:159], v17 offset:17888
	ds_read_b128 v[160:163], v17 offset:18144
	ds_read_b128 v[172:175], v17 offset:18912
	ds_read_b128 v[164:167], v17 offset:18400
	ds_read_b128 v[168:171], v17 offset:18656
	v_pk_mul_f32 v[20:21], v[2:3], v[180:181] op_sel_hi:[0,1]
	v_pk_fma_f32 v[20:21], v[182:183], v[2:3], v[20:21] op_sel:[0,1,0]
	v_pk_fma_f32 v[20:21], v[184:185], v[4:5], v[20:21] op_sel_hi:[1,0,1]
	v_pk_fma_f32 v[20:21], v[186:187], v[4:5], v[20:21] op_sel:[0,1,0]
	v_pk_mul_f32 v[22:23], v[196:197], v[200:201] op_sel_hi:[1,0]
	v_pk_mul_f32 v[24:25], v[198:199], v[200:201] op_sel_hi:[1,0]
	v_add_f32_dpp v26, v20, v20 row_ror:8 row_mask:0xf bank_mask:0xf bound_ctrl:1
	v_add_f32_dpp v28, v21, v21 row_ror:8 row_mask:0xf bank_mask:0xf bound_ctrl:1
	v_pk_fma_f32 v[22:23], v[2:3], v[188:189], v[22:23]
	v_add_f32_dpp v26, v26, v26 row_ror:4 row_mask:0xf bank_mask:0xf bound_ctrl:1
	v_pk_fma_f32 v[24:25], v[4:5], v[190:191], v[24:25]
	v_add_f32_dpp v28, v28, v28 row_ror:4 row_mask:0xf bank_mask:0xf bound_ctrl:1
	v_add_f32_dpp v26, v26, v26 row_ror:2 row_mask:0xf bank_mask:0xf bound_ctrl:1
	ds_read_b32 v176, v18 offset:19168
	ds_read_b64 v[178:179], v19 offset:19232
	v_add_f32_dpp v26, v26, v26 row_ror:1 row_mask:0xf bank_mask:0xf bound_ctrl:1
	v_pk_fma_f32 v[2:3], v[192:193], v[26:27], v[22:23] op_sel_hi:[1,0,1]
	v_pk_fma_f32 v[4:5], v[194:195], v[26:27], v[24:25] op_sel_hi:[1,0,1]
	v_mul_f32_e32 v29, v202, v26
	v_fmac_f32_e32 v29, v200, v203
	v_fmac_f32_e32 v28, 0x3e800000, v29
	ds_write_b32 v9, v28 offset:704
	s_waitcnt lgkmcnt(9)
	ds_read_b128 v[180:183], v17 offset:19264
	ds_read_b128 v[184:187], v17 offset:19520
	ds_read_b128 v[196:199], v17 offset:20288
	ds_read_b128 v[188:191], v17 offset:19776
	ds_read_b128 v[192:195], v17 offset:20032
	v_pk_mul_f32 v[20:21], v[2:3], v[100:101] op_sel_hi:[0,1]
	v_pk_fma_f32 v[20:21], v[102:103], v[2:3], v[20:21] op_sel:[0,1,0]
	v_pk_fma_f32 v[20:21], v[104:105], v[4:5], v[20:21] op_sel_hi:[1,0,1]
	v_pk_fma_f32 v[20:21], v[106:107], v[4:5], v[20:21] op_sel:[0,1,0]
	v_pk_mul_f32 v[22:23], v[116:117], v[120:121] op_sel_hi:[1,0]
	v_pk_mul_f32 v[24:25], v[118:119], v[120:121] op_sel_hi:[1,0]
	v_add_f32_dpp v26, v20, v20 row_ror:8 row_mask:0xf bank_mask:0xf bound_ctrl:1
	v_add_f32_dpp v28, v21, v21 row_ror:8 row_mask:0xf bank_mask:0xf bound_ctrl:1
	v_pk_fma_f32 v[22:23], v[2:3], v[108:109], v[22:23]
	v_add_f32_dpp v26, v26, v26 row_ror:4 row_mask:0xf bank_mask:0xf bound_ctrl:1
	v_pk_fma_f32 v[24:25], v[4:5], v[110:111], v[24:25]
	v_add_f32_dpp v28, v28, v28 row_ror:4 row_mask:0xf bank_mask:0xf bound_ctrl:1
	v_add_f32_dpp v26, v26, v26 row_ror:2 row_mask:0xf bank_mask:0xf bound_ctrl:1
	ds_read_b32 v200, v18 offset:20544
	ds_read_b64 v[202:203], v19 offset:20608
	v_add_f32_dpp v26, v26, v26 row_ror:1 row_mask:0xf bank_mask:0xf bound_ctrl:1
	v_pk_fma_f32 v[2:3], v[112:113], v[26:27], v[22:23] op_sel_hi:[1,0,1]
	v_pk_fma_f32 v[4:5], v[114:115], v[26:27], v[24:25] op_sel_hi:[1,0,1]
	v_mul_f32_e32 v29, v122, v26
	v_fmac_f32_e32 v29, v120, v123
	v_fmac_f32_e32 v28, 0x3e800000, v29
	ds_write_b32 v9, v28 offset:768
	s_waitcnt lgkmcnt(9)
	ds_read_b128 v[100:103], v17 offset:20640
	ds_read_b128 v[104:107], v17 offset:20896
	ds_read_b128 v[116:119], v17 offset:21664
	ds_read_b128 v[108:111], v17 offset:21152
	ds_read_b128 v[112:115], v17 offset:21408
	v_pk_mul_f32 v[20:21], v[2:3], v[156:157] op_sel_hi:[0,1]
	v_pk_fma_f32 v[20:21], v[158:159], v[2:3], v[20:21] op_sel:[0,1,0]
	v_pk_fma_f32 v[20:21], v[160:161], v[4:5], v[20:21] op_sel_hi:[1,0,1]
	v_pk_fma_f32 v[20:21], v[162:163], v[4:5], v[20:21] op_sel:[0,1,0]
	v_pk_mul_f32 v[22:23], v[172:173], v[176:177] op_sel_hi:[1,0]
	v_pk_mul_f32 v[24:25], v[174:175], v[176:177] op_sel_hi:[1,0]
	v_add_f32_dpp v26, v20, v20 row_ror:8 row_mask:0xf bank_mask:0xf bound_ctrl:1
	v_add_f32_dpp v28, v21, v21 row_ror:8 row_mask:0xf bank_mask:0xf bound_ctrl:1
	v_pk_fma_f32 v[22:23], v[2:3], v[164:165], v[22:23]
	v_add_f32_dpp v26, v26, v26 row_ror:4 row_mask:0xf bank_mask:0xf bound_ctrl:1
	v_pk_fma_f32 v[24:25], v[4:5], v[166:167], v[24:25]
	v_add_f32_dpp v28, v28, v28 row_ror:4 row_mask:0xf bank_mask:0xf bound_ctrl:1
	v_add_f32_dpp v26, v26, v26 row_ror:2 row_mask:0xf bank_mask:0xf bound_ctrl:1
	ds_read_b32 v120, v18 offset:21920
	ds_read_b64 v[122:123], v19 offset:21984
	v_add_f32_dpp v26, v26, v26 row_ror:1 row_mask:0xf bank_mask:0xf bound_ctrl:1
	v_pk_fma_f32 v[2:3], v[168:169], v[26:27], v[22:23] op_sel_hi:[1,0,1]
	v_pk_fma_f32 v[4:5], v[170:171], v[26:27], v[24:25] op_sel_hi:[1,0,1]
	v_mul_f32_e32 v29, v178, v26
	v_fmac_f32_e32 v29, v176, v179
	v_fmac_f32_e32 v28, 0x3e800000, v29
	ds_write_b32 v9, v28 offset:832
	s_waitcnt lgkmcnt(9)
	ds_read_b128 v[156:159], v17 offset:22016
	ds_read_b128 v[160:163], v17 offset:22272
	ds_read_b128 v[172:175], v17 offset:23040
	ds_read_b128 v[164:167], v17 offset:22528
	ds_read_b128 v[168:171], v17 offset:22784
	v_pk_mul_f32 v[20:21], v[2:3], v[180:181] op_sel_hi:[0,1]
	v_pk_fma_f32 v[20:21], v[182:183], v[2:3], v[20:21] op_sel:[0,1,0]
	v_pk_fma_f32 v[20:21], v[184:185], v[4:5], v[20:21] op_sel_hi:[1,0,1]
	v_pk_fma_f32 v[20:21], v[186:187], v[4:5], v[20:21] op_sel:[0,1,0]
	v_pk_mul_f32 v[22:23], v[196:197], v[200:201] op_sel_hi:[1,0]
	v_pk_mul_f32 v[24:25], v[198:199], v[200:201] op_sel_hi:[1,0]
	v_add_f32_dpp v26, v20, v20 row_ror:8 row_mask:0xf bank_mask:0xf bound_ctrl:1
	v_add_f32_dpp v28, v21, v21 row_ror:8 row_mask:0xf bank_mask:0xf bound_ctrl:1
	v_pk_fma_f32 v[22:23], v[2:3], v[188:189], v[22:23]
	v_add_f32_dpp v26, v26, v26 row_ror:4 row_mask:0xf bank_mask:0xf bound_ctrl:1
	v_pk_fma_f32 v[24:25], v[4:5], v[190:191], v[24:25]
	v_add_f32_dpp v28, v28, v28 row_ror:4 row_mask:0xf bank_mask:0xf bound_ctrl:1
	v_add_f32_dpp v26, v26, v26 row_ror:2 row_mask:0xf bank_mask:0xf bound_ctrl:1
	ds_read_b32 v176, v18 offset:23296
	ds_read_b64 v[178:179], v19 offset:23360
	v_add_f32_dpp v26, v26, v26 row_ror:1 row_mask:0xf bank_mask:0xf bound_ctrl:1
	v_pk_fma_f32 v[2:3], v[192:193], v[26:27], v[22:23] op_sel_hi:[1,0,1]
	v_pk_fma_f32 v[4:5], v[194:195], v[26:27], v[24:25] op_sel_hi:[1,0,1]
	v_mul_f32_e32 v29, v202, v26
	v_fmac_f32_e32 v29, v200, v203
	v_fmac_f32_e32 v28, 0x3e800000, v29
	ds_write_b32 v9, v28 offset:896
	s_waitcnt lgkmcnt(9)
	ds_read_b128 v[180:183], v17 offset:23392
	ds_read_b128 v[184:187], v17 offset:23648
	ds_read_b128 v[196:199], v17 offset:24416
	ds_read_b128 v[188:191], v17 offset:23904
	ds_read_b128 v[192:195], v17 offset:24160
	v_pk_mul_f32 v[20:21], v[2:3], v[100:101] op_sel_hi:[0,1]
	v_pk_fma_f32 v[20:21], v[102:103], v[2:3], v[20:21] op_sel:[0,1,0]
	v_pk_fma_f32 v[20:21], v[104:105], v[4:5], v[20:21] op_sel_hi:[1,0,1]
	v_pk_fma_f32 v[20:21], v[106:107], v[4:5], v[20:21] op_sel:[0,1,0]
	v_pk_mul_f32 v[22:23], v[116:117], v[120:121] op_sel_hi:[1,0]
	v_pk_mul_f32 v[24:25], v[118:119], v[120:121] op_sel_hi:[1,0]
	v_add_f32_dpp v26, v20, v20 row_ror:8 row_mask:0xf bank_mask:0xf bound_ctrl:1
	v_add_f32_dpp v28, v21, v21 row_ror:8 row_mask:0xf bank_mask:0xf bound_ctrl:1
	v_pk_fma_f32 v[22:23], v[2:3], v[108:109], v[22:23]
	v_add_f32_dpp v26, v26, v26 row_ror:4 row_mask:0xf bank_mask:0xf bound_ctrl:1
	v_pk_fma_f32 v[24:25], v[4:5], v[110:111], v[24:25]
	v_add_f32_dpp v28, v28, v28 row_ror:4 row_mask:0xf bank_mask:0xf bound_ctrl:1
	v_add_f32_dpp v26, v26, v26 row_ror:2 row_mask:0xf bank_mask:0xf bound_ctrl:1
	ds_read_b32 v200, v18 offset:24672
	ds_read_b64 v[202:203], v19 offset:24736
	v_add_f32_dpp v26, v26, v26 row_ror:1 row_mask:0xf bank_mask:0xf bound_ctrl:1
	v_pk_fma_f32 v[2:3], v[112:113], v[26:27], v[22:23] op_sel_hi:[1,0,1]
	v_pk_fma_f32 v[4:5], v[114:115], v[26:27], v[24:25] op_sel_hi:[1,0,1]
	v_mul_f32_e32 v29, v122, v26
	v_fmac_f32_e32 v29, v120, v123
	v_fmac_f32_e32 v28, 0x3e800000, v29
	ds_write_b32 v9, v28 offset:960
	s_waitcnt lgkmcnt(9)
	ds_read_b128 v[100:103], v17 offset:24768
	ds_read_b128 v[104:107], v17 offset:25024
	ds_read_b128 v[116:119], v17 offset:25792
	ds_read_b128 v[108:111], v17 offset:25280
	ds_read_b128 v[112:115], v17 offset:25536
	v_pk_mul_f32 v[20:21], v[2:3], v[156:157] op_sel_hi:[0,1]
	v_pk_fma_f32 v[20:21], v[158:159], v[2:3], v[20:21] op_sel:[0,1,0]
	v_pk_fma_f32 v[20:21], v[160:161], v[4:5], v[20:21] op_sel_hi:[1,0,1]
	v_pk_fma_f32 v[20:21], v[162:163], v[4:5], v[20:21] op_sel:[0,1,0]
	v_pk_mul_f32 v[22:23], v[172:173], v[176:177] op_sel_hi:[1,0]
	v_pk_mul_f32 v[24:25], v[174:175], v[176:177] op_sel_hi:[1,0]
	v_add_f32_dpp v26, v20, v20 row_ror:8 row_mask:0xf bank_mask:0xf bound_ctrl:1
	v_add_f32_dpp v28, v21, v21 row_ror:8 row_mask:0xf bank_mask:0xf bound_ctrl:1
	v_pk_fma_f32 v[22:23], v[2:3], v[164:165], v[22:23]
	v_add_f32_dpp v26, v26, v26 row_ror:4 row_mask:0xf bank_mask:0xf bound_ctrl:1
	v_pk_fma_f32 v[24:25], v[4:5], v[166:167], v[24:25]
	v_add_f32_dpp v28, v28, v28 row_ror:4 row_mask:0xf bank_mask:0xf bound_ctrl:1
	v_add_f32_dpp v26, v26, v26 row_ror:2 row_mask:0xf bank_mask:0xf bound_ctrl:1
	ds_read_b32 v120, v18 offset:26048
	ds_read_b64 v[122:123], v19 offset:26112
	v_add_f32_dpp v26, v26, v26 row_ror:1 row_mask:0xf bank_mask:0xf bound_ctrl:1
	v_pk_fma_f32 v[2:3], v[168:169], v[26:27], v[22:23] op_sel_hi:[1,0,1]
	v_pk_fma_f32 v[4:5], v[170:171], v[26:27], v[24:25] op_sel_hi:[1,0,1]
	v_mul_f32_e32 v29, v178, v26
	v_fmac_f32_e32 v29, v176, v179
	v_fmac_f32_e32 v28, 0x3e800000, v29
	ds_write_b32 v9, v28 offset:1024
	s_waitcnt lgkmcnt(9)
	ds_read_b128 v[156:159], v17 offset:26144
	ds_read_b128 v[160:163], v17 offset:26400
	ds_read_b128 v[172:175], v17 offset:27168
	ds_read_b128 v[164:167], v17 offset:26656
	ds_read_b128 v[168:171], v17 offset:26912
	v_pk_mul_f32 v[20:21], v[2:3], v[180:181] op_sel_hi:[0,1]
	v_pk_fma_f32 v[20:21], v[182:183], v[2:3], v[20:21] op_sel:[0,1,0]
	v_pk_fma_f32 v[20:21], v[184:185], v[4:5], v[20:21] op_sel_hi:[1,0,1]
	v_pk_fma_f32 v[20:21], v[186:187], v[4:5], v[20:21] op_sel:[0,1,0]
	v_pk_mul_f32 v[22:23], v[196:197], v[200:201] op_sel_hi:[1,0]
	v_pk_mul_f32 v[24:25], v[198:199], v[200:201] op_sel_hi:[1,0]
	v_add_f32_dpp v26, v20, v20 row_ror:8 row_mask:0xf bank_mask:0xf bound_ctrl:1
	v_add_f32_dpp v28, v21, v21 row_ror:8 row_mask:0xf bank_mask:0xf bound_ctrl:1
	v_pk_fma_f32 v[22:23], v[2:3], v[188:189], v[22:23]
	v_add_f32_dpp v26, v26, v26 row_ror:4 row_mask:0xf bank_mask:0xf bound_ctrl:1
	v_pk_fma_f32 v[24:25], v[4:5], v[190:191], v[24:25]
	v_add_f32_dpp v28, v28, v28 row_ror:4 row_mask:0xf bank_mask:0xf bound_ctrl:1
	v_add_f32_dpp v26, v26, v26 row_ror:2 row_mask:0xf bank_mask:0xf bound_ctrl:1
	ds_read_b32 v176, v18 offset:27424
	ds_read_b64 v[178:179], v19 offset:27488
	v_add_f32_dpp v26, v26, v26 row_ror:1 row_mask:0xf bank_mask:0xf bound_ctrl:1
	v_pk_fma_f32 v[2:3], v[192:193], v[26:27], v[22:23] op_sel_hi:[1,0,1]
	v_pk_fma_f32 v[4:5], v[194:195], v[26:27], v[24:25] op_sel_hi:[1,0,1]
	v_mul_f32_e32 v29, v202, v26
	v_fmac_f32_e32 v29, v200, v203
	v_fmac_f32_e32 v28, 0x3e800000, v29
	ds_write_b32 v9, v28 offset:1088
	s_waitcnt lgkmcnt(9)
	ds_read_b128 v[180:183], v17 offset:27520
	ds_read_b128 v[184:187], v17 offset:27776
	ds_read_b128 v[196:199], v17 offset:28544
	ds_read_b128 v[188:191], v17 offset:28032
	ds_read_b128 v[192:195], v17 offset:28288
	v_pk_mul_f32 v[20:21], v[2:3], v[100:101] op_sel_hi:[0,1]
	v_pk_fma_f32 v[20:21], v[102:103], v[2:3], v[20:21] op_sel:[0,1,0]
	v_pk_fma_f32 v[20:21], v[104:105], v[4:5], v[20:21] op_sel_hi:[1,0,1]
	v_pk_fma_f32 v[20:21], v[106:107], v[4:5], v[20:21] op_sel:[0,1,0]
	v_pk_mul_f32 v[22:23], v[116:117], v[120:121] op_sel_hi:[1,0]
	v_pk_mul_f32 v[24:25], v[118:119], v[120:121] op_sel_hi:[1,0]
	v_add_f32_dpp v26, v20, v20 row_ror:8 row_mask:0xf bank_mask:0xf bound_ctrl:1
	v_add_f32_dpp v28, v21, v21 row_ror:8 row_mask:0xf bank_mask:0xf bound_ctrl:1
	v_pk_fma_f32 v[22:23], v[2:3], v[108:109], v[22:23]
	v_add_f32_dpp v26, v26, v26 row_ror:4 row_mask:0xf bank_mask:0xf bound_ctrl:1
	v_pk_fma_f32 v[24:25], v[4:5], v[110:111], v[24:25]
	v_add_f32_dpp v28, v28, v28 row_ror:4 row_mask:0xf bank_mask:0xf bound_ctrl:1
	v_add_f32_dpp v26, v26, v26 row_ror:2 row_mask:0xf bank_mask:0xf bound_ctrl:1
	ds_read_b32 v200, v18 offset:28800
	ds_read_b64 v[202:203], v19 offset:28864
	v_add_f32_dpp v26, v26, v26 row_ror:1 row_mask:0xf bank_mask:0xf bound_ctrl:1
	v_pk_fma_f32 v[2:3], v[112:113], v[26:27], v[22:23] op_sel_hi:[1,0,1]
	v_pk_fma_f32 v[4:5], v[114:115], v[26:27], v[24:25] op_sel_hi:[1,0,1]
	v_mul_f32_e32 v29, v122, v26
	v_fmac_f32_e32 v29, v120, v123
	v_fmac_f32_e32 v28, 0x3e800000, v29
	ds_write_b32 v9, v28 offset:1152
	s_waitcnt lgkmcnt(9)
	ds_read_b128 v[100:103], v17 offset:28896
	ds_read_b128 v[104:107], v17 offset:29152
	ds_read_b128 v[116:119], v17 offset:29920
	ds_read_b128 v[108:111], v17 offset:29408
	ds_read_b128 v[112:115], v17 offset:29664
	v_pk_mul_f32 v[20:21], v[2:3], v[156:157] op_sel_hi:[0,1]
	v_pk_fma_f32 v[20:21], v[158:159], v[2:3], v[20:21] op_sel:[0,1,0]
	v_pk_fma_f32 v[20:21], v[160:161], v[4:5], v[20:21] op_sel_hi:[1,0,1]
	v_pk_fma_f32 v[20:21], v[162:163], v[4:5], v[20:21] op_sel:[0,1,0]
	v_pk_mul_f32 v[22:23], v[172:173], v[176:177] op_sel_hi:[1,0]
	v_pk_mul_f32 v[24:25], v[174:175], v[176:177] op_sel_hi:[1,0]
	v_add_f32_dpp v26, v20, v20 row_ror:8 row_mask:0xf bank_mask:0xf bound_ctrl:1
	v_add_f32_dpp v28, v21, v21 row_ror:8 row_mask:0xf bank_mask:0xf bound_ctrl:1
	v_pk_fma_f32 v[22:23], v[2:3], v[164:165], v[22:23]
	v_add_f32_dpp v26, v26, v26 row_ror:4 row_mask:0xf bank_mask:0xf bound_ctrl:1
	v_pk_fma_f32 v[24:25], v[4:5], v[166:167], v[24:25]
	v_add_f32_dpp v28, v28, v28 row_ror:4 row_mask:0xf bank_mask:0xf bound_ctrl:1
	v_add_f32_dpp v26, v26, v26 row_ror:2 row_mask:0xf bank_mask:0xf bound_ctrl:1
	ds_read_b32 v120, v18 offset:30176
	ds_read_b64 v[122:123], v19 offset:30240
	v_add_f32_dpp v26, v26, v26 row_ror:1 row_mask:0xf bank_mask:0xf bound_ctrl:1
	v_pk_fma_f32 v[2:3], v[168:169], v[26:27], v[22:23] op_sel_hi:[1,0,1]
	v_pk_fma_f32 v[4:5], v[170:171], v[26:27], v[24:25] op_sel_hi:[1,0,1]
	v_mul_f32_e32 v29, v178, v26
	v_fmac_f32_e32 v29, v176, v179
	v_fmac_f32_e32 v28, 0x3e800000, v29
	ds_write_b32 v9, v28 offset:1216
	s_waitcnt lgkmcnt(9)
	ds_read_b128 v[156:159], v17 offset:30272
	ds_read_b128 v[160:163], v17 offset:30528
	ds_read_b128 v[172:175], v17 offset:31296
	ds_read_b128 v[164:167], v17 offset:30784
	ds_read_b128 v[168:171], v17 offset:31040
	v_pk_mul_f32 v[20:21], v[2:3], v[180:181] op_sel_hi:[0,1]
	v_pk_fma_f32 v[20:21], v[182:183], v[2:3], v[20:21] op_sel:[0,1,0]
	v_pk_fma_f32 v[20:21], v[184:185], v[4:5], v[20:21] op_sel_hi:[1,0,1]
	v_pk_fma_f32 v[20:21], v[186:187], v[4:5], v[20:21] op_sel:[0,1,0]
	v_pk_mul_f32 v[22:23], v[196:197], v[200:201] op_sel_hi:[1,0]
	v_pk_mul_f32 v[24:25], v[198:199], v[200:201] op_sel_hi:[1,0]
	v_add_f32_dpp v26, v20, v20 row_ror:8 row_mask:0xf bank_mask:0xf bound_ctrl:1
	v_add_f32_dpp v28, v21, v21 row_ror:8 row_mask:0xf bank_mask:0xf bound_ctrl:1
	v_pk_fma_f32 v[22:23], v[2:3], v[188:189], v[22:23]
	v_add_f32_dpp v26, v26, v26 row_ror:4 row_mask:0xf bank_mask:0xf bound_ctrl:1
	v_pk_fma_f32 v[24:25], v[4:5], v[190:191], v[24:25]
	v_add_f32_dpp v28, v28, v28 row_ror:4 row_mask:0xf bank_mask:0xf bound_ctrl:1
	v_add_f32_dpp v26, v26, v26 row_ror:2 row_mask:0xf bank_mask:0xf bound_ctrl:1
	ds_read_b32 v176, v18 offset:31552
	ds_read_b64 v[178:179], v19 offset:31616
	v_add_f32_dpp v26, v26, v26 row_ror:1 row_mask:0xf bank_mask:0xf bound_ctrl:1
	v_pk_fma_f32 v[2:3], v[192:193], v[26:27], v[22:23] op_sel_hi:[1,0,1]
	v_pk_fma_f32 v[4:5], v[194:195], v[26:27], v[24:25] op_sel_hi:[1,0,1]
	v_mul_f32_e32 v29, v202, v26
	v_fmac_f32_e32 v29, v200, v203
	v_fmac_f32_e32 v28, 0x3e800000, v29
	ds_write_b32 v9, v28 offset:1280
	s_waitcnt lgkmcnt(9)
	ds_read_b128 v[180:183], v17 offset:31648
	ds_read_b128 v[184:187], v17 offset:31904
	ds_read_b128 v[196:199], v17 offset:32672
	ds_read_b128 v[188:191], v17 offset:32160
	ds_read_b128 v[192:195], v17 offset:32416
	v_pk_mul_f32 v[20:21], v[2:3], v[100:101] op_sel_hi:[0,1]
	v_pk_fma_f32 v[20:21], v[102:103], v[2:3], v[20:21] op_sel:[0,1,0]
	v_pk_fma_f32 v[20:21], v[104:105], v[4:5], v[20:21] op_sel_hi:[1,0,1]
	v_pk_fma_f32 v[20:21], v[106:107], v[4:5], v[20:21] op_sel:[0,1,0]
	v_pk_mul_f32 v[22:23], v[116:117], v[120:121] op_sel_hi:[1,0]
	v_pk_mul_f32 v[24:25], v[118:119], v[120:121] op_sel_hi:[1,0]
	v_add_f32_dpp v26, v20, v20 row_ror:8 row_mask:0xf bank_mask:0xf bound_ctrl:1
	v_add_f32_dpp v28, v21, v21 row_ror:8 row_mask:0xf bank_mask:0xf bound_ctrl:1
	v_pk_fma_f32 v[22:23], v[2:3], v[108:109], v[22:23]
	v_add_f32_dpp v26, v26, v26 row_ror:4 row_mask:0xf bank_mask:0xf bound_ctrl:1
	v_pk_fma_f32 v[24:25], v[4:5], v[110:111], v[24:25]
	v_add_f32_dpp v28, v28, v28 row_ror:4 row_mask:0xf bank_mask:0xf bound_ctrl:1
	v_add_f32_dpp v26, v26, v26 row_ror:2 row_mask:0xf bank_mask:0xf bound_ctrl:1
	ds_read_b32 v200, v18 offset:32928
	ds_read_b64 v[202:203], v19 offset:32992
	v_add_f32_dpp v26, v26, v26 row_ror:1 row_mask:0xf bank_mask:0xf bound_ctrl:1
	v_pk_fma_f32 v[2:3], v[112:113], v[26:27], v[22:23] op_sel_hi:[1,0,1]
	v_pk_fma_f32 v[4:5], v[114:115], v[26:27], v[24:25] op_sel_hi:[1,0,1]
	v_mul_f32_e32 v29, v122, v26
	v_fmac_f32_e32 v29, v120, v123
	v_fmac_f32_e32 v28, 0x3e800000, v29
	ds_write_b32 v9, v28 offset:1344
	s_waitcnt lgkmcnt(9)
	ds_read_b128 v[100:103], v17 offset:33024
	ds_read_b128 v[104:107], v17 offset:33280
	ds_read_b128 v[116:119], v17 offset:34048
	ds_read_b128 v[108:111], v17 offset:33536
	ds_read_b128 v[112:115], v17 offset:33792
	v_pk_mul_f32 v[20:21], v[2:3], v[156:157] op_sel_hi:[0,1]
	v_pk_fma_f32 v[20:21], v[158:159], v[2:3], v[20:21] op_sel:[0,1,0]
	v_pk_fma_f32 v[20:21], v[160:161], v[4:5], v[20:21] op_sel_hi:[1,0,1]
	v_pk_fma_f32 v[20:21], v[162:163], v[4:5], v[20:21] op_sel:[0,1,0]
	v_pk_mul_f32 v[22:23], v[172:173], v[176:177] op_sel_hi:[1,0]
	v_pk_mul_f32 v[24:25], v[174:175], v[176:177] op_sel_hi:[1,0]
	v_add_f32_dpp v26, v20, v20 row_ror:8 row_mask:0xf bank_mask:0xf bound_ctrl:1
	v_add_f32_dpp v28, v21, v21 row_ror:8 row_mask:0xf bank_mask:0xf bound_ctrl:1
	v_pk_fma_f32 v[22:23], v[2:3], v[164:165], v[22:23]
	v_add_f32_dpp v26, v26, v26 row_ror:4 row_mask:0xf bank_mask:0xf bound_ctrl:1
	v_pk_fma_f32 v[24:25], v[4:5], v[166:167], v[24:25]
	v_add_f32_dpp v28, v28, v28 row_ror:4 row_mask:0xf bank_mask:0xf bound_ctrl:1
	v_add_f32_dpp v26, v26, v26 row_ror:2 row_mask:0xf bank_mask:0xf bound_ctrl:1
	ds_read_b32 v120, v18 offset:34304
	ds_read_b64 v[122:123], v19 offset:34368
	v_add_f32_dpp v26, v26, v26 row_ror:1 row_mask:0xf bank_mask:0xf bound_ctrl:1
	v_pk_fma_f32 v[2:3], v[168:169], v[26:27], v[22:23] op_sel_hi:[1,0,1]
	v_pk_fma_f32 v[4:5], v[170:171], v[26:27], v[24:25] op_sel_hi:[1,0,1]
	v_mul_f32_e32 v29, v178, v26
	v_fmac_f32_e32 v29, v176, v179
	v_fmac_f32_e32 v28, 0x3e800000, v29
	ds_write_b32 v9, v28 offset:1408
	s_waitcnt lgkmcnt(9)
	ds_read_b128 v[156:159], v17 offset:34400
	ds_read_b128 v[160:163], v17 offset:34656
	ds_read_b128 v[172:175], v17 offset:35424
	ds_read_b128 v[164:167], v17 offset:34912
	ds_read_b128 v[168:171], v17 offset:35168
	v_pk_mul_f32 v[20:21], v[2:3], v[180:181] op_sel_hi:[0,1]
	v_pk_fma_f32 v[20:21], v[182:183], v[2:3], v[20:21] op_sel:[0,1,0]
	v_pk_fma_f32 v[20:21], v[184:185], v[4:5], v[20:21] op_sel_hi:[1,0,1]
	v_pk_fma_f32 v[20:21], v[186:187], v[4:5], v[20:21] op_sel:[0,1,0]
	v_pk_mul_f32 v[22:23], v[196:197], v[200:201] op_sel_hi:[1,0]
	v_pk_mul_f32 v[24:25], v[198:199], v[200:201] op_sel_hi:[1,0]
	v_add_f32_dpp v26, v20, v20 row_ror:8 row_mask:0xf bank_mask:0xf bound_ctrl:1
	v_add_f32_dpp v28, v21, v21 row_ror:8 row_mask:0xf bank_mask:0xf bound_ctrl:1
	v_pk_fma_f32 v[22:23], v[2:3], v[188:189], v[22:23]
	v_add_f32_dpp v26, v26, v26 row_ror:4 row_mask:0xf bank_mask:0xf bound_ctrl:1
	v_pk_fma_f32 v[24:25], v[4:5], v[190:191], v[24:25]
	v_add_f32_dpp v28, v28, v28 row_ror:4 row_mask:0xf bank_mask:0xf bound_ctrl:1
	v_add_f32_dpp v26, v26, v26 row_ror:2 row_mask:0xf bank_mask:0xf bound_ctrl:1
	ds_read_b32 v176, v18 offset:35680
	ds_read_b64 v[178:179], v19 offset:35744
	v_add_f32_dpp v26, v26, v26 row_ror:1 row_mask:0xf bank_mask:0xf bound_ctrl:1
	v_pk_fma_f32 v[2:3], v[192:193], v[26:27], v[22:23] op_sel_hi:[1,0,1]
	v_pk_fma_f32 v[4:5], v[194:195], v[26:27], v[24:25] op_sel_hi:[1,0,1]
	v_mul_f32_e32 v29, v202, v26
	v_fmac_f32_e32 v29, v200, v203
	v_fmac_f32_e32 v28, 0x3e800000, v29
	ds_write_b32 v9, v28 offset:1472
	s_waitcnt lgkmcnt(9)
	ds_read_b128 v[180:183], v17 offset:35776
	ds_read_b128 v[184:187], v17 offset:36032
	ds_read_b128 v[196:199], v17 offset:36800
	ds_read_b128 v[188:191], v17 offset:36288
	ds_read_b128 v[192:195], v17 offset:36544
	v_pk_mul_f32 v[20:21], v[2:3], v[100:101] op_sel_hi:[0,1]
	v_pk_fma_f32 v[20:21], v[102:103], v[2:3], v[20:21] op_sel:[0,1,0]
	v_pk_fma_f32 v[20:21], v[104:105], v[4:5], v[20:21] op_sel_hi:[1,0,1]
	v_pk_fma_f32 v[20:21], v[106:107], v[4:5], v[20:21] op_sel:[0,1,0]
	v_pk_mul_f32 v[22:23], v[116:117], v[120:121] op_sel_hi:[1,0]
	v_pk_mul_f32 v[24:25], v[118:119], v[120:121] op_sel_hi:[1,0]
	v_add_f32_dpp v26, v20, v20 row_ror:8 row_mask:0xf bank_mask:0xf bound_ctrl:1
	v_add_f32_dpp v28, v21, v21 row_ror:8 row_mask:0xf bank_mask:0xf bound_ctrl:1
	v_pk_fma_f32 v[22:23], v[2:3], v[108:109], v[22:23]
	v_add_f32_dpp v26, v26, v26 row_ror:4 row_mask:0xf bank_mask:0xf bound_ctrl:1
	v_pk_fma_f32 v[24:25], v[4:5], v[110:111], v[24:25]
	v_add_f32_dpp v28, v28, v28 row_ror:4 row_mask:0xf bank_mask:0xf bound_ctrl:1
	v_add_f32_dpp v26, v26, v26 row_ror:2 row_mask:0xf bank_mask:0xf bound_ctrl:1
	ds_read_b32 v200, v18 offset:37056
	ds_read_b64 v[202:203], v19 offset:37120
	v_add_f32_dpp v26, v26, v26 row_ror:1 row_mask:0xf bank_mask:0xf bound_ctrl:1
	v_pk_fma_f32 v[2:3], v[112:113], v[26:27], v[22:23] op_sel_hi:[1,0,1]
	v_pk_fma_f32 v[4:5], v[114:115], v[26:27], v[24:25] op_sel_hi:[1,0,1]
	v_mul_f32_e32 v29, v122, v26
	v_fmac_f32_e32 v29, v120, v123
	v_fmac_f32_e32 v28, 0x3e800000, v29
	ds_write_b32 v9, v28 offset:1536
	s_waitcnt lgkmcnt(9)
	ds_read_b128 v[100:103], v17 offset:37152
	ds_read_b128 v[104:107], v17 offset:37408
	ds_read_b128 v[116:119], v17 offset:38176
	ds_read_b128 v[108:111], v17 offset:37664
	ds_read_b128 v[112:115], v17 offset:37920
	v_pk_mul_f32 v[20:21], v[2:3], v[156:157] op_sel_hi:[0,1]
	v_pk_fma_f32 v[20:21], v[158:159], v[2:3], v[20:21] op_sel:[0,1,0]
	v_pk_fma_f32 v[20:21], v[160:161], v[4:5], v[20:21] op_sel_hi:[1,0,1]
	v_pk_fma_f32 v[20:21], v[162:163], v[4:5], v[20:21] op_sel:[0,1,0]
	v_pk_mul_f32 v[22:23], v[172:173], v[176:177] op_sel_hi:[1,0]
	v_pk_mul_f32 v[24:25], v[174:175], v[176:177] op_sel_hi:[1,0]
	v_add_f32_dpp v26, v20, v20 row_ror:8 row_mask:0xf bank_mask:0xf bound_ctrl:1
	v_add_f32_dpp v28, v21, v21 row_ror:8 row_mask:0xf bank_mask:0xf bound_ctrl:1
	v_pk_fma_f32 v[22:23], v[2:3], v[164:165], v[22:23]
	v_add_f32_dpp v26, v26, v26 row_ror:4 row_mask:0xf bank_mask:0xf bound_ctrl:1
	v_pk_fma_f32 v[24:25], v[4:5], v[166:167], v[24:25]
	v_add_f32_dpp v28, v28, v28 row_ror:4 row_mask:0xf bank_mask:0xf bound_ctrl:1
	v_add_f32_dpp v26, v26, v26 row_ror:2 row_mask:0xf bank_mask:0xf bound_ctrl:1
	ds_read_b32 v120, v18 offset:38432
	ds_read_b64 v[122:123], v19 offset:38496
	v_add_f32_dpp v26, v26, v26 row_ror:1 row_mask:0xf bank_mask:0xf bound_ctrl:1
	v_pk_fma_f32 v[2:3], v[168:169], v[26:27], v[22:23] op_sel_hi:[1,0,1]
	v_pk_fma_f32 v[4:5], v[170:171], v[26:27], v[24:25] op_sel_hi:[1,0,1]
	v_mul_f32_e32 v29, v178, v26
	v_fmac_f32_e32 v29, v176, v179
	v_fmac_f32_e32 v28, 0x3e800000, v29
	ds_write_b32 v9, v28 offset:1600
	s_waitcnt lgkmcnt(9)
	ds_read_b128 v[156:159], v17 offset:38528
	ds_read_b128 v[160:163], v17 offset:38784
	ds_read_b128 v[172:175], v17 offset:39552
	ds_read_b128 v[164:167], v17 offset:39040
	ds_read_b128 v[168:171], v17 offset:39296
	v_pk_mul_f32 v[20:21], v[2:3], v[180:181] op_sel_hi:[0,1]
	v_pk_fma_f32 v[20:21], v[182:183], v[2:3], v[20:21] op_sel:[0,1,0]
	v_pk_fma_f32 v[20:21], v[184:185], v[4:5], v[20:21] op_sel_hi:[1,0,1]
	v_pk_fma_f32 v[20:21], v[186:187], v[4:5], v[20:21] op_sel:[0,1,0]
	v_pk_mul_f32 v[22:23], v[196:197], v[200:201] op_sel_hi:[1,0]
	v_pk_mul_f32 v[24:25], v[198:199], v[200:201] op_sel_hi:[1,0]
	v_add_f32_dpp v26, v20, v20 row_ror:8 row_mask:0xf bank_mask:0xf bound_ctrl:1
	v_add_f32_dpp v28, v21, v21 row_ror:8 row_mask:0xf bank_mask:0xf bound_ctrl:1
	v_pk_fma_f32 v[22:23], v[2:3], v[188:189], v[22:23]
	v_add_f32_dpp v26, v26, v26 row_ror:4 row_mask:0xf bank_mask:0xf bound_ctrl:1
	v_pk_fma_f32 v[24:25], v[4:5], v[190:191], v[24:25]
	v_add_f32_dpp v28, v28, v28 row_ror:4 row_mask:0xf bank_mask:0xf bound_ctrl:1
	v_add_f32_dpp v26, v26, v26 row_ror:2 row_mask:0xf bank_mask:0xf bound_ctrl:1
	ds_read_b32 v176, v18 offset:39808
	ds_read_b64 v[178:179], v19 offset:39872
	v_add_f32_dpp v26, v26, v26 row_ror:1 row_mask:0xf bank_mask:0xf bound_ctrl:1
	v_pk_fma_f32 v[2:3], v[192:193], v[26:27], v[22:23] op_sel_hi:[1,0,1]
	v_pk_fma_f32 v[4:5], v[194:195], v[26:27], v[24:25] op_sel_hi:[1,0,1]
	v_mul_f32_e32 v29, v202, v26
	v_fmac_f32_e32 v29, v200, v203
	v_fmac_f32_e32 v28, 0x3e800000, v29
	ds_write_b32 v9, v28 offset:1664
	s_waitcnt lgkmcnt(9)
	ds_read_b128 v[180:183], v17 offset:39904
	ds_read_b128 v[184:187], v17 offset:40160
	ds_read_b128 v[196:199], v17 offset:40928
	ds_read_b128 v[188:191], v17 offset:40416
	ds_read_b128 v[192:195], v17 offset:40672
	v_pk_mul_f32 v[20:21], v[2:3], v[100:101] op_sel_hi:[0,1]
	v_pk_fma_f32 v[20:21], v[102:103], v[2:3], v[20:21] op_sel:[0,1,0]
	v_pk_fma_f32 v[20:21], v[104:105], v[4:5], v[20:21] op_sel_hi:[1,0,1]
	v_pk_fma_f32 v[20:21], v[106:107], v[4:5], v[20:21] op_sel:[0,1,0]
	v_pk_mul_f32 v[22:23], v[116:117], v[120:121] op_sel_hi:[1,0]
	v_pk_mul_f32 v[24:25], v[118:119], v[120:121] op_sel_hi:[1,0]
	v_add_f32_dpp v26, v20, v20 row_ror:8 row_mask:0xf bank_mask:0xf bound_ctrl:1
	v_add_f32_dpp v28, v21, v21 row_ror:8 row_mask:0xf bank_mask:0xf bound_ctrl:1
	v_pk_fma_f32 v[22:23], v[2:3], v[108:109], v[22:23]
	v_add_f32_dpp v26, v26, v26 row_ror:4 row_mask:0xf bank_mask:0xf bound_ctrl:1
	v_pk_fma_f32 v[24:25], v[4:5], v[110:111], v[24:25]
	v_add_f32_dpp v28, v28, v28 row_ror:4 row_mask:0xf bank_mask:0xf bound_ctrl:1
	v_add_f32_dpp v26, v26, v26 row_ror:2 row_mask:0xf bank_mask:0xf bound_ctrl:1
	ds_read_b32 v200, v18 offset:41184
	ds_read_b64 v[202:203], v19 offset:41248
	v_add_f32_dpp v26, v26, v26 row_ror:1 row_mask:0xf bank_mask:0xf bound_ctrl:1
	v_pk_fma_f32 v[2:3], v[112:113], v[26:27], v[22:23] op_sel_hi:[1,0,1]
	v_pk_fma_f32 v[4:5], v[114:115], v[26:27], v[24:25] op_sel_hi:[1,0,1]
	v_mul_f32_e32 v29, v122, v26
	v_fmac_f32_e32 v29, v120, v123
	v_fmac_f32_e32 v28, 0x3e800000, v29
	ds_write_b32 v9, v28 offset:1728
	s_waitcnt lgkmcnt(9)
	ds_read_b128 v[100:103], v17 offset:41280
	ds_read_b128 v[104:107], v17 offset:41536
	ds_read_b128 v[116:119], v17 offset:42304
	ds_read_b128 v[108:111], v17 offset:41792
	ds_read_b128 v[112:115], v17 offset:42048
	v_pk_mul_f32 v[20:21], v[2:3], v[156:157] op_sel_hi:[0,1]
	v_pk_fma_f32 v[20:21], v[158:159], v[2:3], v[20:21] op_sel:[0,1,0]
	v_pk_fma_f32 v[20:21], v[160:161], v[4:5], v[20:21] op_sel_hi:[1,0,1]
	v_pk_fma_f32 v[20:21], v[162:163], v[4:5], v[20:21] op_sel:[0,1,0]
	v_pk_mul_f32 v[22:23], v[172:173], v[176:177] op_sel_hi:[1,0]
	v_pk_mul_f32 v[24:25], v[174:175], v[176:177] op_sel_hi:[1,0]
	v_add_f32_dpp v26, v20, v20 row_ror:8 row_mask:0xf bank_mask:0xf bound_ctrl:1
	v_add_f32_dpp v28, v21, v21 row_ror:8 row_mask:0xf bank_mask:0xf bound_ctrl:1
	v_pk_fma_f32 v[22:23], v[2:3], v[164:165], v[22:23]
	v_add_f32_dpp v26, v26, v26 row_ror:4 row_mask:0xf bank_mask:0xf bound_ctrl:1
	v_pk_fma_f32 v[24:25], v[4:5], v[166:167], v[24:25]
	v_add_f32_dpp v28, v28, v28 row_ror:4 row_mask:0xf bank_mask:0xf bound_ctrl:1
	v_add_f32_dpp v26, v26, v26 row_ror:2 row_mask:0xf bank_mask:0xf bound_ctrl:1
	ds_read_b32 v120, v18 offset:42560
	ds_read_b64 v[122:123], v19 offset:42624
	v_add_f32_dpp v26, v26, v26 row_ror:1 row_mask:0xf bank_mask:0xf bound_ctrl:1
	v_pk_fma_f32 v[2:3], v[168:169], v[26:27], v[22:23] op_sel_hi:[1,0,1]
	v_pk_fma_f32 v[4:5], v[170:171], v[26:27], v[24:25] op_sel_hi:[1,0,1]
	v_mul_f32_e32 v29, v178, v26
	v_fmac_f32_e32 v29, v176, v179
	v_fmac_f32_e32 v28, 0x3e800000, v29
	ds_write_b32 v9, v28 offset:1792
	s_waitcnt lgkmcnt(9)
	ds_read_b128 v[156:159], v17 offset:42656
	ds_read_b128 v[160:163], v17 offset:42912
	ds_read_b128 v[172:175], v17 offset:43680
	ds_read_b128 v[164:167], v17 offset:43168
	ds_read_b128 v[168:171], v17 offset:43424
	v_pk_mul_f32 v[20:21], v[2:3], v[180:181] op_sel_hi:[0,1]
	v_pk_fma_f32 v[20:21], v[182:183], v[2:3], v[20:21] op_sel:[0,1,0]
	v_pk_fma_f32 v[20:21], v[184:185], v[4:5], v[20:21] op_sel_hi:[1,0,1]
	v_pk_fma_f32 v[20:21], v[186:187], v[4:5], v[20:21] op_sel:[0,1,0]
	v_pk_mul_f32 v[22:23], v[196:197], v[200:201] op_sel_hi:[1,0]
	v_pk_mul_f32 v[24:25], v[198:199], v[200:201] op_sel_hi:[1,0]
	v_add_f32_dpp v26, v20, v20 row_ror:8 row_mask:0xf bank_mask:0xf bound_ctrl:1
	v_add_f32_dpp v28, v21, v21 row_ror:8 row_mask:0xf bank_mask:0xf bound_ctrl:1
	v_pk_fma_f32 v[22:23], v[2:3], v[188:189], v[22:23]
	v_add_f32_dpp v26, v26, v26 row_ror:4 row_mask:0xf bank_mask:0xf bound_ctrl:1
	v_pk_fma_f32 v[24:25], v[4:5], v[190:191], v[24:25]
	v_add_f32_dpp v28, v28, v28 row_ror:4 row_mask:0xf bank_mask:0xf bound_ctrl:1
	v_add_f32_dpp v26, v26, v26 row_ror:2 row_mask:0xf bank_mask:0xf bound_ctrl:1
	ds_read_b32 v176, v18 offset:43936
	ds_read_b64 v[178:179], v19 offset:44000
	v_add_f32_dpp v26, v26, v26 row_ror:1 row_mask:0xf bank_mask:0xf bound_ctrl:1
	v_pk_fma_f32 v[2:3], v[192:193], v[26:27], v[22:23] op_sel_hi:[1,0,1]
	v_pk_fma_f32 v[4:5], v[194:195], v[26:27], v[24:25] op_sel_hi:[1,0,1]
	v_mul_f32_e32 v29, v202, v26
	v_fmac_f32_e32 v29, v200, v203
	v_fmac_f32_e32 v28, 0x3e800000, v29
	ds_write_b32 v9, v28 offset:1856
	s_waitcnt lgkmcnt(9)
	v_pk_mul_f32 v[20:21], v[2:3], v[100:101] op_sel_hi:[0,1]
	v_pk_fma_f32 v[20:21], v[102:103], v[2:3], v[20:21] op_sel:[0,1,0]
	v_pk_fma_f32 v[20:21], v[104:105], v[4:5], v[20:21] op_sel_hi:[1,0,1]
	v_pk_fma_f32 v[20:21], v[106:107], v[4:5], v[20:21] op_sel:[0,1,0]
	v_pk_mul_f32 v[22:23], v[116:117], v[120:121] op_sel_hi:[1,0]
	v_pk_mul_f32 v[24:25], v[118:119], v[120:121] op_sel_hi:[1,0]
	v_add_f32_dpp v26, v20, v20 row_ror:8 row_mask:0xf bank_mask:0xf bound_ctrl:1
	v_add_f32_dpp v28, v21, v21 row_ror:8 row_mask:0xf bank_mask:0xf bound_ctrl:1
	v_pk_fma_f32 v[22:23], v[2:3], v[108:109], v[22:23]
	v_add_f32_dpp v26, v26, v26 row_ror:4 row_mask:0xf bank_mask:0xf bound_ctrl:1
	v_pk_fma_f32 v[24:25], v[4:5], v[110:111], v[24:25]
	v_add_f32_dpp v28, v28, v28 row_ror:4 row_mask:0xf bank_mask:0xf bound_ctrl:1
	v_add_f32_dpp v26, v26, v26 row_ror:2 row_mask:0xf bank_mask:0xf bound_ctrl:1
	s_nop 1
	v_add_f32_dpp v26, v26, v26 row_ror:1 row_mask:0xf bank_mask:0xf bound_ctrl:1
	v_pk_fma_f32 v[2:3], v[112:113], v[26:27], v[22:23] op_sel_hi:[1,0,1]
	v_pk_fma_f32 v[4:5], v[114:115], v[26:27], v[24:25] op_sel_hi:[1,0,1]
	v_mul_f32_e32 v29, v122, v26
	v_fmac_f32_e32 v29, v120, v123
	v_fmac_f32_e32 v28, 0x3e800000, v29
	ds_write_b32 v9, v28 offset:1920
	s_waitcnt lgkmcnt(2)
	v_pk_mul_f32 v[20:21], v[2:3], v[156:157] op_sel_hi:[0,1]
	v_pk_fma_f32 v[20:21], v[158:159], v[2:3], v[20:21] op_sel:[0,1,0]
	v_pk_fma_f32 v[20:21], v[160:161], v[4:5], v[20:21] op_sel_hi:[1,0,1]
	v_pk_fma_f32 v[20:21], v[162:163], v[4:5], v[20:21] op_sel:[0,1,0]
	v_pk_mul_f32 v[22:23], v[172:173], v[176:177] op_sel_hi:[1,0]
	v_pk_mul_f32 v[24:25], v[174:175], v[176:177] op_sel_hi:[1,0]
	v_add_f32_dpp v26, v20, v20 row_ror:8 row_mask:0xf bank_mask:0xf bound_ctrl:1
	v_add_f32_dpp v28, v21, v21 row_ror:8 row_mask:0xf bank_mask:0xf bound_ctrl:1
	v_pk_fma_f32 v[22:23], v[2:3], v[164:165], v[22:23]
	v_add_f32_dpp v26, v26, v26 row_ror:4 row_mask:0xf bank_mask:0xf bound_ctrl:1
	v_pk_fma_f32 v[24:25], v[4:5], v[166:167], v[24:25]
	v_add_f32_dpp v28, v28, v28 row_ror:4 row_mask:0xf bank_mask:0xf bound_ctrl:1
	v_add_f32_dpp v26, v26, v26 row_ror:2 row_mask:0xf bank_mask:0xf bound_ctrl:1
	s_nop 1
	v_add_f32_dpp v26, v26, v26 row_ror:1 row_mask:0xf bank_mask:0xf bound_ctrl:1
	v_pk_fma_f32 v[2:3], v[168:169], v[26:27], v[22:23] op_sel_hi:[1,0,1]
	v_pk_fma_f32 v[4:5], v[170:171], v[26:27], v[24:25] op_sel_hi:[1,0,1]
	v_mul_f32_e32 v29, v178, v26
	v_fmac_f32_e32 v29, v176, v179
	v_fmac_f32_e32 v28, 0x3e800000, v29
	ds_write_b32 v9, v28 offset:1984
	ds_read_b128 v[30:33], v13
	ds_read_b128 v[34:37], v13 offset:16
	s_add_i32 s4, s4, 32
	s_waitcnt lgkmcnt(0)
	v_add_f32_e32 v38, v30, v31
	v_add_f32_e32 v39, v32, v33
	v_add_f32_e32 v40, v34, v35
	v_add_f32_e32 v41, v36, v37
	v_add_f32_e32 v38, v38, v39
	v_add_f32_e32 v40, v40, v41
	v_cvt_pk_bf16_f32 v6, v38, v40
	global_store_dword v[0:1], v6, off
	v_lshl_add_u64 v[0:1], v[0:1], 0, s[14:15]
	s_cmpk_eq_i32 s4, 0x800
	s_cbranch_scc0 .LBB0_1252
	s_mov_b64 s[4:5], 0

.LBB0_1257:
	s_or_b64 exec, exec, s[4:5]
	s_add_u32 s58, s34, 0xbb00000
	s_addc_u32 s59, s35, 0
	v_mov_b64_e32 v[84:85], s[58:59]
	v_mad_i64_i32 v[84:85], s[4:5], v143, s68, v[84:85]
	v_lshl_add_u64 v[106:107], v[84:85], 0, v[100:101]
	global_load_dwordx4 v[84:87], v[106:107], off
	global_load_dwordx4 v[102:105], v[106:107], off offset:1024
	s_waitcnt vmcnt(8)
	v_mov_b32_e32 v91, v33
	s_waitcnt vmcnt(3)
	v_lshlrev_b32_e32 v112, 16, v52
	v_and_b32_e32 v113, 0xffff0000, v52
	v_and_b32_e32 v52, 64, v142
	v_lshlrev_b32_e32 v108, 16, v58
	v_and_b32_e32 v109, 0xffff0000, v58
	v_lshlrev_b32_e32 v116, 16, v54
	v_and_b32_e32 v118, 0xffff0000, v54
	v_lshlrev_b32_e32 v58, 16, v55
	v_and_b32_e32 v54, 0xffff0000, v55
	v_mov_b32_e32 v33, v36
	v_xor_b32_e32 v55, 1, v142
	v_mov_b32_e32 v36, v91
	v_add_u32_e32 v91, 64, v52
	v_lshlrev_b32_e32 v110, 16, v59
	v_and_b32_e32 v111, 0xffff0000, v59
	v_xor_b32_e32 v59, 2, v142
	v_cmp_lt_i32_e32 vcc, v55, v91
	v_xor_b32_e32 v94, 4, v142
	v_lshlrev_b32_e32 v106, 16, v56
	v_cndmask_b32_e32 v55, v142, v55, vcc
	v_cmp_lt_i32_e32 vcc, v59, v91
	v_and_b32_e32 v107, 0xffff0000, v56
	v_lshlrev_b32_e32 v56, 16, v57
	v_cndmask_b32_e32 v59, v142, v59, vcc
	v_cmp_lt_i32_e32 vcc, v94, v91
	v_and_b32_e32 v57, 0xffff0000, v57
	v_pk_add_f32 v[76:77], v[76:77], v[106:107] neg_lo:[0,1] neg_hi:[0,1]
	v_cndmask_b32_e32 v91, v142, v94, vcc
	v_pk_add_f32 v[74:75], v[74:75], v[56:57] neg_lo:[0,1] neg_hi:[0,1]
	v_pk_fma_f32 v[76:77], v[12:13], v[76:77], v[106:107]
	v_lshlrev_b32_e32 v146, 2, v91
	v_lshlrev_b32_e32 v114, 16, v53
	v_and_b32_e32 v115, 0xffff0000, v53
	v_pk_add_f32 v[52:53], v[78:79], v[112:113] neg_lo:[0,1] neg_hi:[0,1]
	v_pk_fma_f32 v[74:75], v[14:15], v[74:75], v[56:57]
	v_sub_f32_e32 v83, v83, v54
	v_mov_b32_e32 v92, v35
	v_pk_fma_f32 v[78:79], v[28:29], v[52:53], v[112:113]
	v_lshlrev_b32_e32 v144, 2, v55
	v_sub_f32_e32 v82, v82, v58
	v_mov_b32_e32 v35, v38
	v_mov_b32_e32 v38, v92
	v_lshlrev_b32_e32 v145, 2, v59
	v_sub_f32_e32 v81, v81, v118
	v_pk_add_f32 v[70:71], v[70:71], v[114:115] neg_lo:[0,1] neg_hi:[0,1]
	v_sub_f32_e32 v80, v80, v116
	v_pk_add_f32 v[72:73], v[72:73], v[108:109] neg_lo:[0,1] neg_hi:[0,1]
	v_pk_fma_f32 v[70:71], v[30:31], v[70:71], v[114:115]
	v_pk_fma_f32 v[72:73], v[8:9], v[72:73], v[108:109]
	v_pk_mul_f32 v[114:115], v[42:43], v[70:71]
	v_mov_b32_e32 v107, v70
	v_pk_mul_f32 v[130:131], v[114:115], v[114:115]
	v_mul_lo_u32 v96, v98, s65
	v_add_u32_e32 v147, 0, v96
	v_pk_add_f32 v[68:69], v[68:69], v[110:111] neg_lo:[0,1] neg_hi:[0,1]
	v_mov_b32_e32 v109, v71
	v_pk_fma_f32 v[68:69], v[10:11], v[68:69], v[110:111]
	s_and_b32 s41, s64, 3
	s_waitcnt vmcnt(1)
	v_lshlrev_b32_e32 v91, 16, v86
	s_waitcnt vmcnt(0)
	v_lshlrev_b32_e32 v106, 16, v103
	v_and_b32_e32 v94, 0xffff0000, v87
	v_lshlrev_b32_e32 v56, 16, v102
	v_and_b32_e32 v57, 0xffff0000, v102
	v_add_f32_e32 v102, -1.0, v106
	v_mul_f32_e32 v91, 0xbfb8aa3b, v91
	v_lshlrev_b32_e32 v52, 16, v84
	v_and_b32_e32 v53, 0xffff0000, v84
	v_and_b32_e32 v55, 0xffff0000, v105
	v_fma_f32 v113, v46, v102, 1.0
	v_exp_f32_e32 v102, v91
	v_mul_f32_e32 v91, 0xbfb8aa3b, v94
	v_mul_f32_e32 v94, v27, v83
	v_lshlrev_b32_e32 v92, 16, v87
	v_lshlrev_b32_e32 v59, 16, v105
	v_mul_f32_e32 v87, 0xbfb8aa3b, v52
	v_mul_f32_e32 v99, 0xbfb8aa3b, v53
	v_pk_add_f32 v[52:53], v[56:57], -1.0 op_sel_hi:[1,0]
	v_pk_add_f32 v[126:127], v[94:95], v[54:55]
	v_mul_f32_e32 v94, v26, v82
	v_and_b32_e32 v119, 0xffff0000, v104
	v_pk_fma_f32 v[52:53], v[44:45], v[52:53], 1.0 op_sel_hi:[1,1,0]
	v_pk_add_f32 v[134:135], v[94:95], v[58:59]
	v_mul_f32_e32 v94, v25, v81
	v_lshlrev_b32_e32 v84, 16, v85
	v_and_b32_e32 v85, 0xffff0000, v85
	v_and_b32_e32 v86, 0xffff0000, v86
	v_lshlrev_b32_e32 v117, 16, v104
	v_pk_mul_f32 v[52:53], v[78:79], v[52:53]
	v_pk_mul_f32 v[78:79], v[40:41], v[78:79]
	v_pk_add_f32 v[138:139], v[94:95], v[118:119]
	v_mul_f32_e32 v94, v24, v80
	v_and_b32_e32 v108, 0xffff0000, v103
	v_mul_f32_e32 v103, 0xbfb8aa3b, v85
	v_mul_f32_e32 v105, 0xbfb8aa3b, v86
	v_pk_mul_f32 v[132:133], v[78:79], v[78:79]
	v_pk_add_f32 v[80:81], v[94:95], v[116:117]
	v_mul_f32_e32 v101, 0xbfb8aa3b, v84
	v_exp_f32_e32 v84, v87
	v_exp_f32_e32 v87, v103
	v_exp_f32_e32 v103, v105
	v_exp_f32_e32 v105, v91
	v_pk_mul_f32 v[140:141], v[36:37], v[138:139]
	v_pk_mul_f32 v[150:151], v[32:33], v[80:81]
	v_add_f32_e32 v91, v132, v133
	v_mov_b32_e32 v148, v150
	v_mov_b32_e32 v149, v140
	v_add_f32_e32 v91, v91, v130
	v_pk_mul_f32 v[128:129], v[38:39], v[126:127]
	v_pk_mul_f32 v[136:137], v[34:35], v[134:135]
	v_pk_mul_f32 v[148:149], v[148:149], v[148:149]
	v_add_f32_e32 v91, v91, v131
	v_mov_b32_e32 v82, v136
	v_mov_b32_e32 v83, v128
	v_add_f32_e32 v91, v91, v148
	v_pk_mul_f32 v[82:83], v[82:83], v[82:83]
	v_add_f32_e32 v91, v91, v149
	v_add_f32_e32 v82, v91, v82
	v_add_f32_e32 v82, v82, v83
	ds_bpermute_b32 v83, v144, v82
	v_add_f32_e32 v104, -1.0, v108
	v_mul_f32_e32 v92, 0xbfb8aa3b, v92
	v_exp_f32_e32 v85, v99
	v_exp_f32_e32 v86, v101
	s_waitcnt lgkmcnt(0)
	v_add_f32_e32 v82, v82, v83
	ds_bpermute_b32 v83, v145, v82
	v_fma_f32 v121, v47, v104, 1.0
	v_exp_f32_e32 v104, v92
	v_lshlrev_b32_e32 v148, 6, v89
	v_add_u32_e32 v92, v147, v148
	s_waitcnt lgkmcnt(0)
	v_add_f32_e32 v82, v82, v83
	ds_bpermute_b32 v83, v146, v82
	v_lshlrev_b32_e32 v91, 5, v89
	v_sub_u32_e32 v94, v92, v91
	v_pk_mul_f32 v[122:123], v[76:77], v[84:85]
	ds_write_b128 v94, v[84:87] offset:512
	ds_write_b128 v94, v[102:105] offset:528
	s_waitcnt lgkmcnt(2)
	v_add_f32_e32 v70, v82, v83
	v_add_f32_e32 v70, 0x2b8cbccc, v70
	v_rsq_f32_e32 v96, v70
	v_pk_mov_b32 v[84:85], v[116:117], v[80:81] op_sel:[1,0]
	v_pk_fma_f32 v[80:81], v[32:33], v[80:81], s[2:3]
	v_pk_mul_f32 v[124:125], v[74:75], v[86:87]
	v_pk_mul_f32 v[116:117], v[150:151], v[96:97]
	v_pk_fma_f32 v[86:87], v[36:37], v[138:139], s[2:3]
	v_mov_b32_e32 v117, v81
	v_pk_mul_f32 v[80:81], v[116:117], v[84:85]
	v_pk_mul_f32 v[84:85], v[140:141], v[96:97]
	v_pk_mov_b32 v[82:83], v[118:119], v[138:139] op_sel:[1,0]
	v_mov_b32_e32 v85, v87
	v_pk_mul_f32 v[132:133], v[68:69], v[104:105]
	v_pk_mul_f32 v[114:115], v[114:115], v[96:97] op_sel_hi:[1,0]
	v_pk_mul_f32 v[82:83], v[84:85], v[82:83]
	v_xor_b32_e32 v104, 0x80000000, v84
	v_pk_mul_f32 v[86:87], v[136:137], v[96:97]
	v_pk_fma_f32 v[84:85], v[34:35], v[134:135], s[2:3]
	v_mov_b32_e32 v112, v114
	v_mov_b32_e32 v87, v85
	v_pk_mov_b32 v[58:59], v[58:59], v[134:135] op_sel:[1,0]
	v_pk_mul_f32 v[130:131], v[72:73], v[102:103]
	v_pk_mul_f32 v[102:103], v[78:79], v[96:97] op_sel_hi:[1,0]
	v_pk_mul_f32 v[70:71], v[112:113], v[106:107]
	v_mov_b32_e32 v120, v115
	v_pk_mul_f32 v[84:85], v[86:87], v[58:59]
	v_xor_b32_e32 v106, 0x80000000, v86
	v_pk_mul_f32 v[58:59], v[128:129], v[96:97]
	v_pk_fma_f32 v[86:87], v[38:39], v[126:127], s[2:3]
	v_pk_mul_f32 v[78:79], v[120:121], v[108:109]
	v_mov_b32_e32 v59, v87
	v_pk_mov_b32 v[54:55], v[54:55], v[126:127] op_sel:[1,0]
	v_xor_b32_e32 v112, 0x80000000, v103
	v_xor_b32_e32 v110, 0x80000000, v102
	v_mov_b32_e32 v111, v122
	v_mov_b32_e32 v113, v123
	v_pk_mul_f32 v[56:57], v[102:103], v[56:57]
	v_pk_mul_f32 v[86:87], v[58:59], v[54:55]
	v_xor_b32_e32 v108, 0x80000000, v58
	ds_write_b128 v94, v[110:113]
	v_xor_b32_e32 v112, 0x80000000, v115
	v_xor_b32_e32 v110, 0x80000000, v114
	v_mov_b32_e32 v111, v124
	v_mov_b32_e32 v113, v125
	v_mov_b32_e32 v58, v70
	v_mov_b32_e32 v59, v78
	v_mov_b32_e32 v54, v71
	v_mov_b32_e32 v55, v79
	v_xor_b32_e32 v102, 0x80000000, v116
	v_mov_b32_e32 v103, v130
	v_mov_b32_e32 v105, v131
	ds_write_b128 v94, v[110:113] offset:256
	ds_write_b128 v94, v[56:59] offset:768
	ds_write_b128 v94, v[52:55] offset:1024
	ds_write_b128 v94, v[102:105] offset:16
	v_mov_b32_e32 v107, v132
	v_mov_b32_e32 v109, v133
	v_mov_b32_e32 v102, v80
	v_mov_b32_e32 v103, v82
	v_mov_b32_e32 v104, v84
	v_mov_b32_e32 v105, v86
	v_lshrrev_b32_e32 v54, 1, v89
	ds_write_b128 v94, v[106:109] offset:272
	ds_write_b128 v94, v[102:105] offset:784
	v_mov_b32_e32 v102, v81
	v_mov_b32_e32 v103, v83
	v_mov_b32_e32 v104, v85
	v_mov_b32_e32 v105, v87
	v_cmp_eq_u32_e64 s[4:5], s41, v54
	v_and_b32_e32 v149, 8, v90
	ds_write_b128 v94, v[102:105] offset:1040
	s_and_saveexec_b64 s[6:7], s[4:5]
	s_cbranch_execz .LBB0_1259
	v_lshlrev_b32_e32 v54, 16, v48
	v_and_b32_e32 v55, 0xffff0000, v48
	v_lshlrev_b32_e32 v58, 16, v49
	v_and_b32_e32 v59, 0xffff0000, v49
	v_lshlrev_b32_e32 v102, 16, v50
	v_and_b32_e32 v103, 0xffff0000, v50
	v_lshlrev_b32_e32 v104, 16, v51
	v_and_b32_e32 v105, 0xffff0000, v51
	v_pk_add_f32 v[48:49], v[62:63], v[54:55] neg_lo:[0,1] neg_hi:[0,1]
	v_pk_add_f32 v[50:51], v[66:67], v[58:59] neg_lo:[0,1] neg_hi:[0,1]
	v_lshl_add_u32 v90, v149, 2, v147
	v_pk_fma_f32 v[48:49], v[16:17], v[48:49], v[54:55]
	v_pk_fma_f32 v[50:51], v[18:19], v[50:51], v[58:59]
	ds_write_b128 v90, v[48:51] offset:1280
	v_pk_add_f32 v[48:49], v[60:61], v[102:103] neg_lo:[0,1] neg_hi:[0,1]
	v_pk_add_f32 v[50:51], v[64:65], v[104:105] neg_lo:[0,1] neg_hi:[0,1]
	v_pk_fma_f32 v[48:49], v[20:21], v[48:49], v[102:103]
	v_pk_fma_f32 v[50:51], v[22:23], v[50:51], v[104:105]
	ds_write_b128 v90, v[48:51] offset:1296

.LBB0_1262:
	s_or_b64 exec, exec, s[38:39]
	s_cmp_lt_i32 s64, s40
	s_load_dwordx2 s[44:45], s[8:9], 0x8
	s_cselect_b64 s[38:39], -1, 0
	s_add_i32 s72, s10, -4
	s_mulk_i32 s10, 0x2200
	s_add_i32 s10, s10, 0
	v_lshlrev_b32_e32 v92, 3, v88
	s_add_i32 s10, s10, 0xf000
	v_lshl_add_u64 v[48:49], s[34:35], 0, v[92:93]
	s_cmp_eq_u32 s41, 0
	v_lshl_add_u64 v[102:103], v[48:49], 0, s[18:19]
	v_lshlrev_b32_e32 v48, 4, v88
	v_mov_b32_e32 v49, v93
	s_cselect_b64 s[40:41], -1, 0
	s_lshl_b32 s61, s42, 3
	s_load_dwordx2 s[42:43], s[8:9], 0xd8
	s_waitcnt lgkmcnt(0)
	v_lshl_add_u64 v[48:49], s[44:45], 0, v[48:49]
	s_load_dwordx2 s[44:45], s[8:9], 0x120
	s_load_dwordx4 s[48:51], s[8:9], 0x108
	s_load_dwordx8 s[76:83], s[8:9], 0xe8
	v_lshl_add_u64 v[104:105], v[48:49], 0, s[26:27]
	v_lshrrev_b32_e32 v151, 3, v88
	s_waitcnt lgkmcnt(0)
	s_add_u32 s44, s44, 0x100000
	s_addc_u32 s45, s45, 0
	s_add_u32 s46, s50, 0x400000
	s_addc_u32 s47, s51, 0
	s_add_u32 s48, s48, 0x1000
	s_addc_u32 s49, s49, 0
	s_add_u32 s50, s82, 0xb00000
	s_addc_u32 s51, s83, 0
	s_add_u32 s52, s80, 0xb00000
	s_addc_u32 s53, s81, 0
	s_add_u32 s54, s76, 0x1000
	s_addc_u32 s55, s77, 0
	s_add_u32 s56, s78, 0xb00000
	s_addc_u32 s57, s79, 0
	s_or_b32 s8, s61, s60
	s_ashr_i32 s9, s8, 31
	s_lshl_b64 s[8:9], s[8:9], 13
	v_lshlrev_b32_e32 v48, 2, v88
	v_and_b32_e32 v52, 56, v92
	s_add_u32 s8, s34, s8
	v_and_b32_e32 v50, 28, v48
	v_mul_u32_u24_e32 v48, 0x84, v52
	v_lshlrev_b32_e32 v49, 2, v151
	v_ashrrev_i32_e32 v99, 31, v98
	s_addc_u32 s9, s35, s9
	v_add3_u32 v158, s10, v48, v49
	v_lshl_add_u64 v[48:49], v[98:99], 2, s[8:9]
	v_lshl_add_u32 v51, v50, 2, s10
	v_mul_u32_u24_e32 v53, 0x84, v151
	v_mov_b32_e32 v106, v100
	v_mov_b32_e32 v107, v93
	v_lshl_add_u64 v[110:111], v[48:49], 0, s[28:29]
	v_mov_b32_e32 v48, 0
	v_sub_u32_e32 v150, 0, v91
	s_mov_b32 s73, 0
	v_or_b32_e32 v152, 8, v151
	v_or_b32_e32 v153, 16, v151
	v_or_b32_e32 v156, 24, v151
	v_bfe_u32 v157, v88, 3, 2
	v_lshl_add_u64 v[108:109], s[58:59], 0, v[106:107]
	v_add_u32_e32 v99, v51, v53
	v_lshlrev_b32_e32 v112, 1, v52
	v_lshlrev_b32_e32 v92, 2, v50
	s_mov_b32 s74, 0
	v_mov_b32_e32 v49, v48
	v_mov_b32_e32 v50, v48
	v_mov_b32_e32 v51, v48
	v_mov_b32_e32 v52, v48
	v_mov_b32_e32 v53, v48
	v_mov_b32_e32 v54, v48
	v_mov_b32_e32 v55, v48
	v_mov_b32_e32 v56, v48
	v_mov_b32_e32 v57, v48
	v_mov_b32_e32 v58, v48
	v_mov_b32_e32 v59, v48
	v_mov_b32_e32 v60, v48
	v_mov_b32_e32 v61, v48
	v_mov_b32_e32 v62, v48
	v_mov_b32_e32 v63, v48
	v_mov_b32_e32 v64, v48
	v_mov_b32_e32 v65, v48
	v_mov_b32_e32 v66, v48
	v_mov_b32_e32 v67, v48
	v_mov_b32_e32 v68, v48
	v_mov_b32_e32 v69, v48
	v_mov_b32_e32 v70, v48
	v_mov_b32_e32 v71, v48
	v_mov_b32_e32 v76, v48
	v_mov_b32_e32 v77, v48
	v_mov_b32_e32 v78, v48
	v_mov_b32_e32 v79, v48
	v_mov_b32_e32 v72, v48
	v_mov_b32_e32 v73, v48
	v_mov_b32_e32 v74, v48
	v_mov_b32_e32 v75, v48
	s_mov_b32 s94, 0x3c000
	s_mov_b32 s95, 0
	s_mov_b32 s96, 0x18000
	s_mov_b32 s97, 0
	s_mov_b32 s98, 0xffffe200
	s_mov_b32 s99, -1
	v_add_u32_e32 v242, 32, v143
	v_mov_b64_e32 v[236:237], s[36:37]
	v_mad_i64_i32 v[236:237], s[8:9], v242, s67, v[236:237]
	v_lshl_add_u64 v[236:237], v[236:237], 0, v[106:107]
	v_add_co_u32_e32 v236, vcc, 0x1000, v236
	s_nop 1
	v_addc_co_u32_e32 v237, vcc, 0, v237, vcc
	v_lshl_add_u64 v[238:239], v[236:237], 0, s[98:99]
	v_mad_i64_i32 v[240:241], s[8:9], v242, s68, v[108:109]
	global_load_dwordx4 v[204:207], v[236:237], off
	global_load_dwordx4 v[208:211], v[236:237], off offset:1024
	global_load_dwordx4 v[212:215], v[236:237], off offset:2048
	global_load_dwordx4 v[216:219], v[238:239], off
	global_load_dwordx4 v[220:223], v[238:239], off offset:1024
	global_load_dwordx4 v[224:227], v[238:239], off offset:2048
	global_load_dwordx4 v[228:231], v[240:241], off
	global_load_dwordx4 v[232:235], v[240:241], off offset:1024
	v_lshl_add_u64 v[236:237], v[236:237], 0, s[94:95]
	v_lshl_add_u64 v[238:239], v[238:239], 0, s[94:95]
	v_lshl_add_u64 v[240:241], v[240:241], 0, s[96:97]
	s_branch .LBB0_1265

.LBB0_1265:
	s_waitcnt lgkmcnt(0)
	s_barrier
	s_waitcnt vmcnt(0)
	v_mov_b32_e32 v88, v204
	v_mov_b32_e32 v89, v205
	v_mov_b32_e32 v90, v206
	v_mov_b32_e32 v91, v207
	v_mov_b32_e32 v84, v208
	v_mov_b32_e32 v85, v209
	v_mov_b32_e32 v86, v210
	v_mov_b32_e32 v87, v211
	v_mov_b32_e32 v80, v212
	v_mov_b32_e32 v81, v213
	v_mov_b32_e32 v82, v214
	v_mov_b32_e32 v83, v215
	v_lshlrev_b32_e32 v130, 16, v216
	v_and_b32_e32 v131, 0xffff0000, v216
	v_lshlrev_b32_e32 v128, 16, v217
	v_and_b32_e32 v129, 0xffff0000, v217
	v_lshlrev_b32_e32 v126, 16, v218
	v_and_b32_e32 v127, 0xffff0000, v218
	v_lshlrev_b32_e32 v122, 16, v219
	v_and_b32_e32 v123, 0xffff0000, v219
	v_lshlrev_b32_e32 v132, 16, v220
	v_and_b32_e32 v133, 0xffff0000, v220
	v_lshlrev_b32_e32 v124, 16, v221
	v_and_b32_e32 v125, 0xffff0000, v221
	v_lshlrev_b32_e32 v96, 16, v222
	v_and_b32_e32 v94, 0xffff0000, v222
	v_lshlrev_b32_e32 v101, 16, v223
	v_and_b32_e32 v113, 0xffff0000, v223
	v_lshlrev_b32_e32 v116, 16, v224
	v_and_b32_e32 v117, 0xffff0000, v224
	v_lshlrev_b32_e32 v120, 16, v225
	v_and_b32_e32 v121, 0xffff0000, v225
	v_lshlrev_b32_e32 v114, 16, v226
	v_and_b32_e32 v115, 0xffff0000, v226
	v_lshlrev_b32_e32 v118, 16, v227
	v_and_b32_e32 v119, 0xffff0000, v227
	v_mov_b32_e32 v134, v228
	v_mov_b32_e32 v135, v229
	v_mov_b32_e32 v136, v230
	v_mov_b32_e32 v137, v231
	v_mov_b32_e32 v138, v232
	v_mov_b32_e32 v139, v233
	v_mov_b32_e32 v140, v234
	v_mov_b32_e32 v141, v235
	s_cmpk_eq_i32 s73, 0x7c0
	s_cbranch_scc1 .Lscan_pf_skip
	global_load_dwordx4 v[204:207], v[236:237], off
	global_load_dwordx4 v[208:211], v[236:237], off offset:1024
	global_load_dwordx4 v[212:215], v[236:237], off offset:2048
	global_load_dwordx4 v[216:219], v[238:239], off
	global_load_dwordx4 v[220:223], v[238:239], off offset:1024
	global_load_dwordx4 v[224:227], v[238:239], off offset:2048
	global_load_dwordx4 v[228:231], v[240:241], off
	global_load_dwordx4 v[232:235], v[240:241], off offset:1024
	v_lshl_add_u64 v[236:237], v[236:237], 0, s[94:95]
	v_lshl_add_u64 v[238:239], v[238:239], 0, s[94:95]
	v_lshl_add_u64 v[240:241], v[240:241], 0, s[96:97]
.Lscan_pf_skip:
	v_and_b32_e32 v172, 0xffff0000, v87
	v_and_b32_e32 v168, 0xffff0000, v86
	v_lshlrev_b32_e32 v170, 16, v87
	v_sub_f32_e32 v113, v113, v172
	v_sub_f32_e32 v101, v101, v170
	v_sub_f32_e32 v159, v94, v168
	v_mul_f32_e32 v94, v27, v113
	v_lshlrev_b32_e32 v164, 16, v84
	v_and_b32_e32 v165, 0xffff0000, v84
	v_lshlrev_b32_e32 v160, 16, v88
	v_and_b32_e32 v161, 0xffff0000, v88
	v_lshlrev_b32_e32 v162, 16, v90
	v_and_b32_e32 v163, 0xffff0000, v90
	v_lshlrev_b32_e32 v84, 16, v85
	v_and_b32_e32 v85, 0xffff0000, v85
	v_lshlrev_b32_e32 v166, 16, v86
	v_pk_add_f32 v[86:87], v[132:133], v[164:165] neg_lo:[0,1] neg_hi:[0,1]
	v_lshlrev_b32_e32 v88, 16, v89
	v_and_b32_e32 v89, 0xffff0000, v89
	v_pk_add_f32 v[130:131], v[130:131], v[160:161] neg_lo:[0,1] neg_hi:[0,1]
	v_pk_add_f32 v[174:175], v[126:127], v[162:163] neg_lo:[0,1] neg_hi:[0,1]
	v_pk_add_f32 v[176:177], v[124:125], v[84:85] neg_lo:[0,1] neg_hi:[0,1]
	v_pk_fma_f32 v[164:165], v[28:29], v[86:87], v[164:165]
	v_pk_add_f32 v[132:133], v[128:129], v[88:89] neg_lo:[0,1] neg_hi:[0,1]
	v_pk_fma_f32 v[128:129], v[12:13], v[130:131], v[160:161]
	v_pk_fma_f32 v[124:125], v[8:9], v[174:175], v[162:163]
	v_pk_fma_f32 v[160:161], v[30:31], v[176:177], v[84:85]
	v_pk_mul_f32 v[174:175], v[40:41], v[164:165]
	v_pk_mul_f32 v[162:163], v[42:43], v[160:161]
	v_pk_mul_f32 v[176:177], v[174:175], v[174:175]
	v_pk_fma_f32 v[126:127], v[14:15], v[132:133], v[88:89]
	v_pk_mul_f32 v[132:133], v[162:163], v[162:163]
	v_lshlrev_b32_e32 v90, 16, v91
	v_and_b32_e32 v91, 0xffff0000, v91
	v_pk_add_f32 v[122:123], v[122:123], v[90:91] neg_lo:[0,1] neg_hi:[0,1]
	s_add_i32 s73, s73, 32
	v_pk_fma_f32 v[122:123], v[10:11], v[122:123], v[90:91]
	s_and_b32 s8, s73, 32
	s_mulk_i32 s8, 0x560
	v_lshlrev_b32_e32 v84, 16, v134
	v_and_b32_e32 v173, 0xffff0000, v141
	v_lshlrev_b32_e32 v171, 16, v141
	v_pk_add_f32 v[178:179], v[94:95], v[172:173]
	v_mul_f32_e32 v94, v26, v101
	v_and_b32_e32 v169, 0xffff0000, v140
	v_pk_add_f32 v[184:185], v[94:95], v[170:171]
	v_mul_f32_e32 v94, v25, v159
	v_pk_add_f32 v[194:195], v[94:95], v[168:169]
	v_sub_f32_e32 v94, v96, v166
	v_lshlrev_b32_e32 v167, 16, v140
	v_mul_f32_e32 v94, v24, v94
	v_and_b32_e32 v85, 0xffff0000, v134
	v_lshlrev_b32_e32 v140, 16, v138
	v_and_b32_e32 v141, 0xffff0000, v138
	v_pk_add_f32 v[198:199], v[94:95], v[166:167]
	v_lshlrev_b32_e32 v88, 16, v136
	v_and_b32_e32 v89, 0xffff0000, v136
	v_mul_f32_e32 v130, 0xbfb8aa3b, v84
	v_mul_f32_e32 v131, 0xbfb8aa3b, v85
	v_pk_add_f32 v[84:85], v[140:141], -1.0 op_sel_hi:[1,0]
	v_pk_mul_f32 v[196:197], v[36:37], v[194:195]
	v_pk_mul_f32 v[200:201], v[32:33], v[198:199]
	v_add_f32_e32 v94, v176, v177
	v_lshlrev_b32_e32 v86, 16, v135
	v_and_b32_e32 v87, 0xffff0000, v135
	v_mul_f32_e32 v182, 0xbfb8aa3b, v88
	v_mul_f32_e32 v183, 0xbfb8aa3b, v89
	v_pk_fma_f32 v[84:85], v[44:45], v[84:85], 1.0 op_sel_hi:[1,1,0]
	v_mov_b32_e32 v202, v200
	v_mov_b32_e32 v203, v196
	v_add_f32_e32 v94, v94, v132
	v_lshlrev_b32_e32 v113, 16, v137
	v_and_b32_e32 v135, 0xffff0000, v137
	v_mul_f32_e32 v137, 0xbfb8aa3b, v86
	v_mul_f32_e32 v180, 0xbfb8aa3b, v87
	v_exp_f32_e32 v86, v130
	v_exp_f32_e32 v87, v131
	v_exp_f32_e32 v130, v182
	v_exp_f32_e32 v131, v183
	v_pk_mul_f32 v[182:183], v[38:39], v[178:179]
	v_pk_mul_f32 v[84:85], v[164:165], v[84:85]
	v_pk_mul_f32 v[164:165], v[34:35], v[184:185]
	v_pk_mul_f32 v[202:203], v[202:203], v[202:203]
	v_add_f32_e32 v94, v94, v133
	v_mov_b32_e32 v187, v182
	v_mov_b32_e32 v186, v164
	v_add_f32_e32 v94, v94, v202
	v_pk_mul_f32 v[186:187], v[186:187], v[186:187]
	v_add_f32_e32 v94, v94, v203
	v_add_f32_e32 v94, v94, v186
	v_add_f32_e32 v94, v94, v187
	v_mul_f32_e32 v101, 0xbfb8aa3b, v135
	v_exp_f32_e32 v133, v101
	v_mul_f32_e32 v113, 0xbfb8aa3b, v113
	v_exp_f32_e32 v88, v137
	v_add_f32_dpp v96, v94, v94 quad_perm:[1,0,3,2] row_mask:0xf bank_mask:0xf
	v_exp_f32_e32 v89, v180
	v_exp_f32_e32 v132, v113
	v_add_u32_e32 v94, s8, v147
	v_add_u32_e32 v113, v94, v148
	v_add_f32_dpp v90, v96, v96 quad_perm:[2,3,0,1] row_mask:0xf bank_mask:0xf
	v_add_u32_e32 v101, v113, v150
	v_pk_mul_f32 v[188:189], v[128:129], v[86:87]
	ds_write_b128 v101, v[86:89] offset:512
	ds_write_b128 v101, v[130:133] offset:528
	v_lshlrev_b32_e32 v134, 16, v139
	v_add_f32_dpp v86, v90, v90 row_half_mirror row_mask:0xf bank_mask:0xf
	v_add_f32_e32 v86, 0x2b8cbccc, v86
	v_rsq_f32_e32 v96, v86
	v_and_b32_e32 v136, 0xffff0000, v139
	v_add_f32_e32 v138, -1.0, v134
	v_add_f32_e32 v181, -1.0, v136
	v_mov_b32_e32 v135, v160
	v_mov_b32_e32 v137, v161
	v_pk_mul_f32 v[160:161], v[174:175], v[96:97] op_sel_hi:[1,0]
	v_pk_mul_f32 v[174:175], v[162:163], v[96:97] op_sel_hi:[1,0]
	v_fma_f32 v139, v46, v138, 1.0
	v_fma_f32 v181, v47, v181, 1.0
	v_mov_b32_e32 v138, v174
	v_mov_b32_e32 v180, v175
	v_pk_mul_f32 v[192:193], v[124:125], v[130:131]
	v_pk_mul_f32 v[176:177], v[122:123], v[132:133]
	v_pk_mul_f32 v[130:131], v[138:139], v[134:135]
	v_pk_mul_f32 v[132:133], v[180:181], v[136:137]
	v_pk_mul_f32 v[180:181], v[200:201], v[96:97]
	v_pk_fma_f32 v[134:135], v[32:33], v[198:199], s[2:3]
	v_pk_mov_b32 v[90:91], v[166:167], v[198:199] op_sel:[1,0]
	v_mov_b32_e32 v181, v135
	v_pk_mul_f32 v[134:135], v[180:181], v[90:91]
	v_pk_mul_f32 v[90:91], v[196:197], v[96:97]
	v_pk_fma_f32 v[136:137], v[36:37], v[194:195], s[2:3]
	v_pk_mov_b32 v[86:87], v[168:169], v[194:195] op_sel:[1,0]
	v_mov_b32_e32 v91, v137
	v_pk_mul_f32 v[136:137], v[90:91], v[86:87]
	v_xor_b32_e32 v162, 0x80000000, v90
	v_pk_mul_f32 v[86:87], v[164:165], v[96:97]
	v_pk_fma_f32 v[90:91], v[34:35], v[184:185], s[2:3]
	v_xor_b32_e32 v164, 0x80000000, v86
	v_mov_b32_e32 v87, v91
	v_pk_mov_b32 v[90:91], v[170:171], v[184:185] op_sel:[1,0]
	v_pk_mul_f32 v[190:191], v[126:127], v[88:89]
	v_pk_mul_f32 v[138:139], v[86:87], v[90:91]
	v_pk_mul_f32 v[86:87], v[182:183], v[96:97]
	v_pk_fma_f32 v[90:91], v[38:39], v[178:179], s[2:3]
	v_xor_b32_e32 v170, 0x80000000, v161
	v_mov_b32_e32 v87, v91
	v_pk_mov_b32 v[90:91], v[172:173], v[178:179] op_sel:[1,0]
	v_xor_b32_e32 v168, 0x80000000, v160
	v_mov_b32_e32 v169, v188
	v_mov_b32_e32 v171, v189
	v_pk_mul_f32 v[88:89], v[160:161], v[140:141]
	v_pk_mul_f32 v[140:141], v[86:87], v[90:91]
	v_xor_b32_e32 v166, 0x80000000, v86
	ds_write_b128 v101, v[168:171]
	v_xor_b32_e32 v170, 0x80000000, v175
	v_xor_b32_e32 v168, 0x80000000, v174
	v_mov_b32_e32 v169, v190
	v_mov_b32_e32 v171, v191
	v_mov_b32_e32 v90, v130
	v_mov_b32_e32 v91, v132
	v_mov_b32_e32 v86, v131
	v_mov_b32_e32 v87, v133
	v_xor_b32_e32 v160, 0x80000000, v180
	v_mov_b32_e32 v161, v192
	v_mov_b32_e32 v163, v193
	ds_write_b128 v101, v[168:171] offset:256
	ds_write_b128 v101, v[88:91] offset:768
	ds_write_b128 v101, v[84:87] offset:1024
	ds_write_b128 v101, v[160:163] offset:16
	v_mov_b32_e32 v165, v176
	v_mov_b32_e32 v167, v177
	v_mov_b32_e32 v160, v134
	v_mov_b32_e32 v161, v136
	v_mov_b32_e32 v162, v138
	v_mov_b32_e32 v163, v140
	ds_write_b128 v101, v[164:167] offset:272
	ds_write_b128 v101, v[160:163] offset:784
	v_mov_b32_e32 v160, v135
	v_mov_b32_e32 v161, v137
	v_mov_b32_e32 v162, v139
	v_mov_b32_e32 v163, v141
	ds_write_b128 v101, v[160:163] offset:1040
	s_and_saveexec_b64 s[8:9], s[4:5]
	s_cbranch_execz .LBB0_1269
	v_lshlrev_b32_e32 v86, 16, v80
	v_and_b32_e32 v87, 0xffff0000, v80
	v_lshlrev_b32_e32 v90, 16, v81
	v_and_b32_e32 v91, 0xffff0000, v81
	v_lshlrev_b32_e32 v160, 16, v82
	v_and_b32_e32 v161, 0xffff0000, v82
	v_lshlrev_b32_e32 v162, 16, v83
	v_and_b32_e32 v163, 0xffff0000, v83
	v_pk_add_f32 v[80:81], v[116:117], v[86:87] neg_lo:[0,1] neg_hi:[0,1]
	v_pk_add_f32 v[82:83], v[120:121], v[90:91] neg_lo:[0,1] neg_hi:[0,1]
	v_lshl_add_u32 v96, v149, 2, v94
	v_pk_fma_f32 v[80:81], v[16:17], v[80:81], v[86:87]
	v_pk_fma_f32 v[82:83], v[18:19], v[82:83], v[90:91]
	ds_write_b128 v96, v[80:83] offset:1280
	v_pk_add_f32 v[80:81], v[114:115], v[160:161] neg_lo:[0,1] neg_hi:[0,1]
	v_pk_add_f32 v[82:83], v[118:119], v[162:163] neg_lo:[0,1] neg_hi:[0,1]
	v_pk_fma_f32 v[80:81], v[20:21], v[80:81], v[160:161]
	v_pk_fma_f32 v[82:83], v[22:23], v[82:83], v[162:163]
	ds_write_b128 v96, v[80:83] offset:1296
.LBB0_1269:
	s_or_b64 exec, exec, s[8:9]
	v_mov_b32_e32 v80, v88
	v_mov_b32_e32 v81, v84
	v_mul_f32_e32 v82, v128, v84
	v_fma_f32 v86, v4, v82, 0
	v_mov_b32_e32 v84, v89
	v_mul_f32_e32 v82, v129, v85
	v_pk_fma_f32 v[80:81], v[128:129], v[80:81], 0 op_sel_hi:[0,1,0]
	v_fmac_f32_e32 v86, v5, v82
	v_mul_f32_e32 v82, v126, v131
	v_pk_fma_f32 v[80:81], v[128:129], v[84:85], v[80:81] op_sel:[1,0,0]
	v_fmac_f32_e32 v86, v6, v82
	v_mul_f32_e32 v82, v127, v133
	v_pk_fma_f32 v[80:81], v[126:127], v[130:131], v[80:81] op_sel_hi:[0,1,1]
	v_fmac_f32_e32 v86, v7, v82
	v_mul_f32_e32 v82, v124, v135
	v_pk_fma_f32 v[80:81], v[126:127], v[132:133], v[80:81] op_sel:[1,0,0]
	v_fmac_f32_e32 v86, v0, v82
	v_mul_f32_e32 v82, v125, v137
	v_pk_fma_f32 v[80:81], v[124:125], v[134:135], v[80:81] op_sel_hi:[0,1,1]
	v_fmac_f32_e32 v86, v1, v82
	v_mul_f32_e32 v82, v122, v139
	v_pk_fma_f32 v[80:81], v[124:125], v[136:137], v[80:81] op_sel:[1,0,0]
	v_fmac_f32_e32 v86, v2, v82
	v_mul_f32_e32 v82, v123, v141
	v_pk_fma_f32 v[80:81], v[122:123], v[138:139], v[80:81] op_sel_hi:[0,1,1]
	v_fmac_f32_e32 v86, v3, v82
	v_pk_fma_f32 v[80:81], v[122:123], v[140:141], v[80:81] op_sel:[1,0,0]
	s_nop 1
	v_add_f32_dpp v84, v86, v86 quad_perm:[1,0,3,2] row_mask:0xf bank_mask:0xf
	v_add_f32_dpp v80, v80, v80 quad_perm:[1,0,3,2] row_mask:0xf bank_mask:0xf
	v_add_f32_dpp v81, v81, v81 quad_perm:[1,0,3,2] row_mask:0xf bank_mask:0xf
	v_add_f32_dpp v84, v84, v84 quad_perm:[2,3,0,1] row_mask:0xf bank_mask:0xf
	v_add_f32_dpp v80, v80, v80 quad_perm:[2,3,0,1] row_mask:0xf bank_mask:0xf
	v_add_f32_dpp v81, v81, v81 quad_perm:[2,3,0,1] row_mask:0xf bank_mask:0xf
	v_add_f32_dpp v84, v84, v84 row_half_mirror row_mask:0xf bank_mask:0xf
	v_add_f32_dpp v80, v80, v80 row_half_mirror row_mask:0xf bank_mask:0xf
	v_add_f32_dpp v81, v81, v81 row_half_mirror row_mask:0xf bank_mask:0xf
	s_and_saveexec_b64 s[8:9], s[6:7]
	s_cbranch_execz .LBB0_1271
	s_andn2_b64 vcc, exec, s[40:41]
	ds_write_b64 v94, v[80:81] offset:1344
	s_cbranch_vccz .LBB0_1292

.LBB0_1292:
	v_mov_b32_e32 v80, v84
	global_store_dword v[110:111], v80, off
	s_or_b64 exec, exec, s[8:9]
	s_andn2_b64 vcc, exec, s[38:39]
	s_cbranch_vccz .LBB0_1272
	s_branch .LBB0_1264

	.amdhsa_kernel _Z9trunk_fwd6Params
		.amdhsa_group_segment_fixed_size 0
		.amdhsa_private_segment_fixed_size 0
		.amdhsa_kernarg_size 576
		.amdhsa_user_sgpr_count 2
		.amdhsa_user_sgpr_dispatch_ptr 0
		.amdhsa_user_sgpr_queue_ptr 0
		.amdhsa_user_sgpr_kernarg_segment_ptr 1
		.amdhsa_user_sgpr_dispatch_id 0
		.amdhsa_user_sgpr_kernarg_preload_length 0
		.amdhsa_user_sgpr_kernarg_preload_offset 0
		.amdhsa_user_sgpr_private_segment_size 0
		.amdhsa_uses_dynamic_stack 0
		.amdhsa_enable_private_segment 0
		.amdhsa_system_sgpr_workgroup_id_x 1
		.amdhsa_system_sgpr_workgroup_id_y 0
		.amdhsa_system_sgpr_workgroup_id_z 0
		.amdhsa_system_sgpr_workgroup_info 0
		.amdhsa_system_vgpr_workitem_id 2
		.amdhsa_next_free_vgpr 256
		.amdhsa_next_free_sgpr 100
		.amdhsa_accum_offset 256
		.amdhsa_reserve_vcc 1
		.amdhsa_float_round_mode_32 0
		.amdhsa_float_round_mode_16_64 0
		.amdhsa_float_denorm_mode_32 3
		.amdhsa_float_denorm_mode_16_64 3
		.amdhsa_dx10_clamp 1
		.amdhsa_ieee_mode 1
		.amdhsa_fp16_overflow 0
		.amdhsa_tg_split 0
		.amdhsa_exception_fp_ieee_invalid_op 0
		.amdhsa_exception_fp_denorm_src 0
		.amdhsa_exception_fp_ieee_div_zero 0
		.amdhsa_exception_fp_ieee_overflow 0
		.amdhsa_exception_fp_ieee_underflow 0
		.amdhsa_exception_fp_ieee_inexact 0
		.amdhsa_exception_int_div_zero 0
	.end_amdhsa_kernel

amdhsa.kernels:
  - .agpr_count:     0
    .args:
      - .offset:         0
        .size:           320
        .value_kind:     by_value
      - .offset:         320
        .size:           4
        .value_kind:     hidden_block_count_x
      - .offset:         324
        .size:           4
        .value_kind:     hidden_block_count_y
      - .offset:         328
        .size:           4
        .value_kind:     hidden_block_count_z
      - .offset:         332
        .size:           2
        .value_kind:     hidden_group_size_x
      - .offset:         334
        .size:           2
        .value_kind:     hidden_group_size_y
      - .offset:         336
        .size:           2
        .value_kind:     hidden_group_size_z
      - .offset:         338
        .size:           2
        .value_kind:     hidden_remainder_x
      - .offset:         340
        .size:           2
        .value_kind:     hidden_remainder_y
      - .offset:         342
        .size:           2
        .value_kind:     hidden_remainder_z
      - .offset:         360
        .size:           8
        .value_kind:     hidden_global_offset_x
      - .offset:         368
        .size:           8
        .value_kind:     hidden_global_offset_y
      - .offset:         376
        .size:           8
        .value_kind:     hidden_global_offset_z
      - .offset:         384
        .size:           2
        .value_kind:     hidden_grid_dims
      - .offset:         408
        .size:           8
        .value_kind:     hidden_multigrid_sync_arg
      - .offset:         440
        .size:           4
        .value_kind:     hidden_dynamic_lds_size
    .group_segment_fixed_size: 0
    .kernarg_segment_align: 8
    .kernarg_segment_size: 576
    .language:       OpenCL C
    .language_version:
      - 2
      - 0
    .max_flat_workgroup_size: 512
    .name:           _Z9trunk_fwd6Params
    .private_segment_fixed_size: 0
    .sgpr_count:     106
    .sgpr_spill_count: 0
    .symbol:         _Z9trunk_fwd6Params.kd
    .uniform_work_group_size: 1
    .uses_dynamic_stack: false
    .vgpr_count:     256
    .vgpr_spill_count: 0
    .wavefront_size: 64
